# removed the per-segment s_setprio 1/0 toggles from the GEMM main loops (144 instructions)
# baseline (speedup 1.0000x reference)
.LBB0_568:
	s_add_u32 s24, s22, 0xfffc0080
	s_addc_u32 s25, s23, -1
	s_add_i32 s53, 0, 0x10000
	s_cmp_eq_u32 s52, 12
	s_cselect_b32 s27, s15, s25
	s_cselect_b32 s26, s42, s24
	s_cselect_b32 s25, s13, s50
	s_cselect_b32 s24, s43, s49
	s_add_i32 s58, 0, 0x14000
	v_add_u32_e32 v154, s53, v143
	v_add_u32_e32 v170, s58, v143
	ds_read_b128 v[138:141], v154
	ds_read_b128 v[146:149], v154 offset:1024
	ds_read_b128 v[150:153], v154 offset:2048
	ds_read_b128 v[154:157], v154 offset:3072
	ds_read_b128 v[158:161], v170
	ds_read_b128 v[162:165], v170 offset:1024
	ds_read_b128 v[166:169], v170 offset:2048
	ds_read_b128 v[170:173], v170 offset:3072
	v_lshl_add_u64 v[174:175], s[22:23], 0, v[136:137]
	s_add_i32 m0, s38, 0xc000
	ds_read_b128 v[178:181], v145
	ds_read_b128 v[186:189], v145 offset:1024
	ds_read_b128 v[190:193], v145 offset:2048
	ds_read_b128 v[194:197], v145 offset:3072
	ds_read_b128 v[198:201], v145 offset:4096
	ds_read_b128 v[202:205], v145 offset:5120
	ds_read_b128 v[206:209], v145 offset:6144
	ds_read_b128 v[210:213], v145 offset:7168
	global_load_lds_dwordx4 v[174:175], off
	v_lshl_add_u64 v[174:175], s[22:23], 0, v[134:135]
	s_add_i32 m0, s38, 0xe000
	s_nop 0
	global_load_lds_dwordx4 v[174:175], off
	s_waitcnt vmcnt(8)
	s_waitcnt lgkmcnt(0)
	s_barrier
	s_waitcnt lgkmcnt(0)
	v_mfma_f32_16x16x32_bf16 v[124:127], v[138:141], v[178:181], v[124:127]
	v_mfma_f32_16x16x32_bf16 v[120:123], v[150:153], v[178:181], v[120:123]
	v_mfma_f32_16x16x32_bf16 v[108:111], v[138:141], v[190:193], v[108:111]
	v_mfma_f32_16x16x32_bf16 v[104:107], v[150:153], v[190:193], v[104:107]
	v_mfma_f32_16x16x32_bf16 v[92:95], v[138:141], v[198:201], v[92:95]
	v_mfma_f32_16x16x32_bf16 v[88:91], v[150:153], v[198:201], v[88:91]
	v_mfma_f32_16x16x32_bf16 v[76:79], v[138:141], v[206:209], v[76:79]
	v_mfma_f32_16x16x32_bf16 v[72:75], v[150:153], v[206:209], v[72:75]
	v_mfma_f32_16x16x32_bf16 v[124:127], v[146:149], v[186:189], v[124:127]
	v_mfma_f32_16x16x32_bf16 v[120:123], v[154:157], v[186:189], v[120:123]
	v_mfma_f32_16x16x32_bf16 v[108:111], v[146:149], v[194:197], v[108:111]
	v_mfma_f32_16x16x32_bf16 v[104:107], v[154:157], v[194:197], v[104:107]
	v_mfma_f32_16x16x32_bf16 v[92:95], v[146:149], v[202:205], v[92:95]
	v_mfma_f32_16x16x32_bf16 v[88:91], v[154:157], v[202:205], v[88:91]
	v_mfma_f32_16x16x32_bf16 v[76:79], v[146:149], v[210:213], v[76:79]
	v_mfma_f32_16x16x32_bf16 v[72:75], v[154:157], v[210:213], v[72:75]
	v_mfma_f32_16x16x32_bf16 v[116:119], v[158:161], v[178:181], v[116:119]
	v_mfma_f32_16x16x32_bf16 v[112:115], v[166:169], v[178:181], v[112:115]
	v_mfma_f32_16x16x32_bf16 v[100:103], v[158:161], v[190:193], v[100:103]
	v_mfma_f32_16x16x32_bf16 v[96:99], v[166:169], v[190:193], v[96:99]
	v_mfma_f32_16x16x32_bf16 v[84:87], v[158:161], v[198:201], v[84:87]
	v_mfma_f32_16x16x32_bf16 v[80:83], v[166:169], v[198:201], v[80:83]
	v_mfma_f32_16x16x32_bf16 v[68:71], v[158:161], v[206:209], v[68:71]
	v_mfma_f32_16x16x32_bf16 v[64:67], v[166:169], v[206:209], v[64:67]
	v_mfma_f32_16x16x32_bf16 v[116:119], v[162:165], v[186:189], v[116:119]
	v_mfma_f32_16x16x32_bf16 v[112:115], v[170:173], v[186:189], v[112:115]
	v_mfma_f32_16x16x32_bf16 v[100:103], v[162:165], v[194:197], v[100:103]
	v_mfma_f32_16x16x32_bf16 v[96:99], v[170:173], v[194:197], v[96:99]
	v_mfma_f32_16x16x32_bf16 v[84:87], v[162:165], v[202:205], v[84:87]
	v_mfma_f32_16x16x32_bf16 v[80:83], v[170:173], v[202:205], v[80:83]
	v_mfma_f32_16x16x32_bf16 v[68:71], v[162:165], v[210:213], v[68:71]
	v_mfma_f32_16x16x32_bf16 v[64:67], v[170:173], v[210:213], v[64:67]
	s_barrier
	s_add_i32 s53, s53, s36
	v_lshl_add_u64 v[174:175], s[24:25], 0, v[176:177]
	s_mov_b32 m0, s53
	ds_read_b128 v[178:181], v145 offset:16384
	ds_read_b128 v[186:189], v145 offset:17408
	ds_read_b128 v[190:193], v145 offset:18432
	ds_read_b128 v[194:197], v145 offset:19456
	ds_read_b128 v[198:201], v145 offset:20480
	ds_read_b128 v[202:205], v145 offset:21504
	ds_read_b128 v[206:209], v145 offset:22528
	ds_read_b128 v[210:213], v145 offset:23552
	global_load_lds_dwordx4 v[174:175], off
	s_add_i32 m0, s53, 0x2000
	s_add_u32 s56, s24, 0x40000
	v_lshl_add_u64 v[214:215], s[24:25], 0, v[128:129]
	s_addc_u32 s57, s25, 0
	s_add_i32 s53, s58, s36
	global_load_lds_dwordx4 v[214:215], off
	v_lshl_add_u64 v[216:217], s[56:57], 0, v[176:177]
	s_mov_b32 m0, s53
	v_lshl_add_u64 v[218:219], s[26:27], 0, v[130:131]
	global_load_lds_dwordx4 v[216:217], off
	v_lshl_add_u64 v[216:217], s[56:57], 0, v[128:129]
	s_add_i32 m0, s53, 0x2000
	s_nop 0
	global_load_lds_dwordx4 v[216:217], off
	v_lshl_add_u64 v[216:217], s[26:27], 0, v[132:133]
	s_mov_b32 m0, s38
	s_nop 0
	global_load_lds_dwordx4 v[216:217], off
	s_mov_b32 m0, s39
	s_nop 0
	global_load_lds_dwordx4 v[218:219], off
	s_waitcnt vmcnt(8)
	s_waitcnt lgkmcnt(0)
	s_barrier
	s_waitcnt lgkmcnt(0)
	v_mfma_f32_16x16x32_bf16 v[60:63], v[138:141], v[178:181], v[60:63]
	v_mfma_f32_16x16x32_bf16 v[56:59], v[150:153], v[178:181], v[56:59]
	v_mfma_f32_16x16x32_bf16 v[44:47], v[138:141], v[190:193], v[44:47]
	v_mfma_f32_16x16x32_bf16 v[40:43], v[150:153], v[190:193], v[40:43]
	v_mfma_f32_16x16x32_bf16 v[28:31], v[138:141], v[198:201], v[28:31]
	v_mfma_f32_16x16x32_bf16 v[24:27], v[150:153], v[198:201], v[24:27]
	v_mfma_f32_16x16x32_bf16 v[12:15], v[138:141], v[206:209], v[12:15]
	v_mfma_f32_16x16x32_bf16 v[8:11], v[150:153], v[206:209], v[8:11]
	v_mfma_f32_16x16x32_bf16 v[60:63], v[146:149], v[186:189], v[60:63]
	v_mfma_f32_16x16x32_bf16 v[56:59], v[154:157], v[186:189], v[56:59]
	v_mfma_f32_16x16x32_bf16 v[44:47], v[146:149], v[194:197], v[44:47]
	v_mfma_f32_16x16x32_bf16 v[40:43], v[154:157], v[194:197], v[40:43]
	v_mfma_f32_16x16x32_bf16 v[28:31], v[146:149], v[202:205], v[28:31]
	v_mfma_f32_16x16x32_bf16 v[24:27], v[154:157], v[202:205], v[24:27]
	v_mfma_f32_16x16x32_bf16 v[12:15], v[146:149], v[210:213], v[12:15]
	v_mfma_f32_16x16x32_bf16 v[8:11], v[154:157], v[210:213], v[8:11]
	v_mfma_f32_16x16x32_bf16 v[52:55], v[158:161], v[178:181], v[52:55]
	v_mfma_f32_16x16x32_bf16 v[48:51], v[166:169], v[178:181], v[48:51]
	v_mfma_f32_16x16x32_bf16 v[36:39], v[158:161], v[190:193], v[36:39]
	v_mfma_f32_16x16x32_bf16 v[32:35], v[166:169], v[190:193], v[32:35]
	v_mfma_f32_16x16x32_bf16 v[20:23], v[158:161], v[198:201], v[20:23]
	v_mfma_f32_16x16x32_bf16 v[16:19], v[166:169], v[198:201], v[16:19]
	v_mfma_f32_16x16x32_bf16 v[4:7], v[158:161], v[206:209], v[4:7]
	v_mfma_f32_16x16x32_bf16 v[0:3], v[166:169], v[206:209], v[0:3]
	v_mfma_f32_16x16x32_bf16 v[52:55], v[162:165], v[186:189], v[52:55]
	v_mfma_f32_16x16x32_bf16 v[48:51], v[170:173], v[186:189], v[48:51]
	v_mfma_f32_16x16x32_bf16 v[36:39], v[162:165], v[194:197], v[36:39]
	v_mfma_f32_16x16x32_bf16 v[32:35], v[170:173], v[194:197], v[32:35]
	v_mfma_f32_16x16x32_bf16 v[20:23], v[162:165], v[202:205], v[20:23]
	v_mfma_f32_16x16x32_bf16 v[16:19], v[170:173], v[202:205], v[16:19]
	v_mfma_f32_16x16x32_bf16 v[4:7], v[162:165], v[210:213], v[4:7]
	v_mfma_f32_16x16x32_bf16 v[0:3], v[170:173], v[210:213], v[0:3]
	s_barrier
	s_add_i32 s53, 0, 0x18000
	s_add_i32 s56, 0, 0x1c000
	v_add_u32_e32 v154, s53, v143
	v_add_u32_e32 v170, s56, v143
	ds_read_b128 v[138:141], v154
	ds_read_b128 v[146:149], v154 offset:1024
	ds_read_b128 v[150:153], v154 offset:2048
	ds_read_b128 v[154:157], v154 offset:3072
	ds_read_b128 v[158:161], v170
	ds_read_b128 v[162:165], v170 offset:1024
	ds_read_b128 v[166:169], v170 offset:2048
	ds_read_b128 v[170:173], v170 offset:3072
	s_add_u32 s26, s26, 0x40000
	s_addc_u32 s27, s27, 0
	s_mov_b32 m0, s40
	v_lshl_add_u64 v[222:223], s[26:27], 0, v[132:133]
	ds_read_b128 v[178:181], v145 offset:32768
	ds_read_b128 v[186:189], v145 offset:33792
	ds_read_b128 v[190:193], v145 offset:34816
	ds_read_b128 v[194:197], v145 offset:35840
	ds_read_b128 v[198:201], v145 offset:36864
	ds_read_b128 v[202:205], v145 offset:37888
	ds_read_b128 v[206:209], v145 offset:38912
	ds_read_b128 v[210:213], v145 offset:39936
	global_load_lds_dwordx4 v[222:223], off
	v_lshl_add_u64 v[222:223], s[26:27], 0, v[130:131]
	s_mov_b32 m0, s41
	s_nop 0
	global_load_lds_dwordx4 v[222:223], off
	s_waitcnt vmcnt(8)
	s_waitcnt lgkmcnt(0)
	s_barrier
	s_waitcnt lgkmcnt(0)
	v_mfma_f32_16x16x32_bf16 v[124:127], v[138:141], v[178:181], v[124:127]
	v_mfma_f32_16x16x32_bf16 v[120:123], v[150:153], v[178:181], v[120:123]
	v_mfma_f32_16x16x32_bf16 v[108:111], v[138:141], v[190:193], v[108:111]
	v_mfma_f32_16x16x32_bf16 v[104:107], v[150:153], v[190:193], v[104:107]
	v_mfma_f32_16x16x32_bf16 v[92:95], v[138:141], v[198:201], v[92:95]
	v_mfma_f32_16x16x32_bf16 v[88:91], v[150:153], v[198:201], v[88:91]
	v_mfma_f32_16x16x32_bf16 v[76:79], v[138:141], v[206:209], v[76:79]
	v_mfma_f32_16x16x32_bf16 v[72:75], v[150:153], v[206:209], v[72:75]
	v_mfma_f32_16x16x32_bf16 v[124:127], v[146:149], v[186:189], v[124:127]
	v_mfma_f32_16x16x32_bf16 v[120:123], v[154:157], v[186:189], v[120:123]
	v_mfma_f32_16x16x32_bf16 v[108:111], v[146:149], v[194:197], v[108:111]
	v_mfma_f32_16x16x32_bf16 v[104:107], v[154:157], v[194:197], v[104:107]
	v_mfma_f32_16x16x32_bf16 v[92:95], v[146:149], v[202:205], v[92:95]
	v_mfma_f32_16x16x32_bf16 v[88:91], v[154:157], v[202:205], v[88:91]
	v_mfma_f32_16x16x32_bf16 v[76:79], v[146:149], v[210:213], v[76:79]
	v_mfma_f32_16x16x32_bf16 v[72:75], v[154:157], v[210:213], v[72:75]
	v_mfma_f32_16x16x32_bf16 v[116:119], v[158:161], v[178:181], v[116:119]
	v_mfma_f32_16x16x32_bf16 v[112:115], v[166:169], v[178:181], v[112:115]
	v_mfma_f32_16x16x32_bf16 v[100:103], v[158:161], v[190:193], v[100:103]
	v_mfma_f32_16x16x32_bf16 v[96:99], v[166:169], v[190:193], v[96:99]
	v_mfma_f32_16x16x32_bf16 v[84:87], v[158:161], v[198:201], v[84:87]
	v_mfma_f32_16x16x32_bf16 v[80:83], v[166:169], v[198:201], v[80:83]
	v_mfma_f32_16x16x32_bf16 v[68:71], v[158:161], v[206:209], v[68:71]
	v_mfma_f32_16x16x32_bf16 v[64:67], v[166:169], v[206:209], v[64:67]
	v_mfma_f32_16x16x32_bf16 v[116:119], v[162:165], v[186:189], v[116:119]
	v_mfma_f32_16x16x32_bf16 v[112:115], v[170:173], v[186:189], v[112:115]
	v_mfma_f32_16x16x32_bf16 v[100:103], v[162:165], v[194:197], v[100:103]
	v_mfma_f32_16x16x32_bf16 v[96:99], v[170:173], v[194:197], v[96:99]
	v_mfma_f32_16x16x32_bf16 v[84:87], v[162:165], v[202:205], v[84:87]
	v_mfma_f32_16x16x32_bf16 v[80:83], v[170:173], v[202:205], v[80:83]
	v_mfma_f32_16x16x32_bf16 v[68:71], v[162:165], v[210:213], v[68:71]
	v_mfma_f32_16x16x32_bf16 v[64:67], v[170:173], v[210:213], v[64:67]
	s_barrier
	s_add_i32 s26, s53, s36
	v_lshl_add_u64 v[174:175], v[174:175], 0, s[72:73]
	s_mov_b32 m0, s26
	ds_read_b128 v[178:181], v145 offset:49152
	ds_read_b128 v[186:189], v145 offset:50176
	ds_read_b128 v[190:193], v145 offset:51200
	ds_read_b128 v[194:197], v145 offset:52224
	ds_read_b128 v[198:201], v145 offset:53248
	ds_read_b128 v[202:205], v145 offset:54272
	ds_read_b128 v[206:209], v145 offset:55296
	ds_read_b128 v[210:213], v145 offset:56320
	global_load_lds_dwordx4 v[174:175], off
	s_add_i32 m0, s26, 0x2000
	s_add_u32 s24, s24, 0x40080
	v_lshl_add_u64 v[174:175], v[214:215], 0, s[72:73]
	s_addc_u32 s25, s25, 0
	s_add_i32 s26, s56, s36
	global_load_lds_dwordx4 v[174:175], off
	v_lshl_add_u64 v[174:175], s[24:25], 0, v[176:177]
	s_mov_b32 m0, s26
	s_nop 0
	global_load_lds_dwordx4 v[174:175], off
	v_lshl_add_u64 v[174:175], s[24:25], 0, v[128:129]
	s_add_i32 m0, s26, 0x2000
	s_nop 0
	global_load_lds_dwordx4 v[174:175], off
	v_lshl_add_u64 v[174:175], v[216:217], 0, s[72:73]
	s_mov_b32 m0, s44
	s_nop 0
	global_load_lds_dwordx4 v[174:175], off
	v_lshl_add_u64 v[174:175], v[218:219], 0, s[72:73]
	s_mov_b32 m0, s45
	s_nop 0
	global_load_lds_dwordx4 v[174:175], off
	s_waitcnt vmcnt(8)
	s_waitcnt lgkmcnt(0)
	s_barrier
	s_waitcnt lgkmcnt(0)
	v_mfma_f32_16x16x32_bf16 v[60:63], v[138:141], v[178:181], v[60:63]
	v_mfma_f32_16x16x32_bf16 v[56:59], v[150:153], v[178:181], v[56:59]
	v_mfma_f32_16x16x32_bf16 v[44:47], v[138:141], v[190:193], v[44:47]
	v_mfma_f32_16x16x32_bf16 v[40:43], v[150:153], v[190:193], v[40:43]
	v_mfma_f32_16x16x32_bf16 v[28:31], v[138:141], v[198:201], v[28:31]
	v_mfma_f32_16x16x32_bf16 v[24:27], v[150:153], v[198:201], v[24:27]
	v_mfma_f32_16x16x32_bf16 v[12:15], v[138:141], v[206:209], v[12:15]
	v_mfma_f32_16x16x32_bf16 v[8:11], v[150:153], v[206:209], v[8:11]
	v_mfma_f32_16x16x32_bf16 v[60:63], v[146:149], v[186:189], v[60:63]
	v_mfma_f32_16x16x32_bf16 v[56:59], v[154:157], v[186:189], v[56:59]
	v_mfma_f32_16x16x32_bf16 v[44:47], v[146:149], v[194:197], v[44:47]
	v_mfma_f32_16x16x32_bf16 v[40:43], v[154:157], v[194:197], v[40:43]
	v_mfma_f32_16x16x32_bf16 v[28:31], v[146:149], v[202:205], v[28:31]
	v_mfma_f32_16x16x32_bf16 v[24:27], v[154:157], v[202:205], v[24:27]
	v_mfma_f32_16x16x32_bf16 v[12:15], v[146:149], v[210:213], v[12:15]
	v_mfma_f32_16x16x32_bf16 v[8:11], v[154:157], v[210:213], v[8:11]
	v_mfma_f32_16x16x32_bf16 v[52:55], v[158:161], v[178:181], v[52:55]
	v_mfma_f32_16x16x32_bf16 v[48:51], v[166:169], v[178:181], v[48:51]
	v_mfma_f32_16x16x32_bf16 v[36:39], v[158:161], v[190:193], v[36:39]
	v_mfma_f32_16x16x32_bf16 v[32:35], v[166:169], v[190:193], v[32:35]
	v_mfma_f32_16x16x32_bf16 v[20:23], v[158:161], v[198:201], v[20:23]
	v_mfma_f32_16x16x32_bf16 v[16:19], v[166:169], v[198:201], v[16:19]
	v_mfma_f32_16x16x32_bf16 v[4:7], v[158:161], v[206:209], v[4:7]
	v_mfma_f32_16x16x32_bf16 v[0:3], v[166:169], v[206:209], v[0:3]
	v_mfma_f32_16x16x32_bf16 v[52:55], v[162:165], v[186:189], v[52:55]
	v_mfma_f32_16x16x32_bf16 v[48:51], v[170:173], v[186:189], v[48:51]
	v_mfma_f32_16x16x32_bf16 v[36:39], v[162:165], v[194:197], v[36:39]
	v_mfma_f32_16x16x32_bf16 v[32:35], v[170:173], v[194:197], v[32:35]
	v_mfma_f32_16x16x32_bf16 v[20:23], v[162:165], v[202:205], v[20:23]
	v_mfma_f32_16x16x32_bf16 v[16:19], v[170:173], v[202:205], v[16:19]
	v_mfma_f32_16x16x32_bf16 v[4:7], v[162:165], v[210:213], v[4:7]
	v_mfma_f32_16x16x32_bf16 v[0:3], v[170:173], v[210:213], v[0:3]
	s_barrier
	s_add_i32 s52, s52, 2
	s_add_u32 s49, s49, 0x100
	s_addc_u32 s50, s50, 0
	s_add_u32 s22, s22, 0x100
	s_addc_u32 s23, s23, 0
	s_cmp_gt_u32 s52, 13
	s_cbranch_scc0 .LBB0_568
	s_and_b64 vcc, exec, s[10:11]
	s_cbranch_vccz .LBB0_571
	s_barrier

.LBB0_588:
	s_add_u32 s26, s24, 0xfffc0080
	s_addc_u32 s27, s25, -1
	s_add_i32 s53, 0, 0x10000
	s_cmp_eq_u32 s50, 12
	s_cselect_b32 s29, s5, s27
	s_cselect_b32 s28, s7, s26
	v_add_u32_e32 v144, s53, v147
	s_cselect_b32 s27, s17, s43
	s_cselect_b32 s26, s19, s42
	s_add_i32 s58, 0, 0x14000
	ds_read_b128 v[140:143], v144
	ds_read_b128 v[150:153], v144 offset:1024
	ds_read_b128 v[154:157], v144 offset:2048
	ds_read_b128 v[158:161], v144 offset:3072
	v_add_u32_e32 v144, s58, v147
	ds_read_b128 v[162:165], v144
	ds_read_b128 v[166:169], v144 offset:1024
	ds_read_b128 v[170:173], v144 offset:2048
	ds_read_b128 v[178:181], v144 offset:3072
	v_lshl_add_u64 v[144:145], s[24:25], 0, v[138:139]
	s_add_i32 m0, s39, 0xc000
	ds_read_b128 v[186:189], v149
	ds_read_b128 v[190:193], v149 offset:1024
	ds_read_b128 v[194:197], v149 offset:2048
	ds_read_b128 v[198:201], v149 offset:3072
	ds_read_b128 v[202:205], v149 offset:4096
	ds_read_b128 v[206:209], v149 offset:5120
	ds_read_b128 v[210:213], v149 offset:6144
	ds_read_b128 v[214:217], v149 offset:7168
	global_load_lds_dwordx4 v[144:145], off
	v_lshl_add_u64 v[144:145], s[24:25], 0, v[136:137]
	s_add_i32 m0, s39, 0xe000
	s_nop 0
	global_load_lds_dwordx4 v[144:145], off
	s_waitcnt vmcnt(8)
	s_waitcnt lgkmcnt(0)
	s_barrier
	s_waitcnt lgkmcnt(0)
	v_mfma_f32_16x16x32_bf16 v[124:127], v[140:143], v[186:189], v[124:127]
	v_mfma_f32_16x16x32_bf16 v[120:123], v[154:157], v[186:189], v[120:123]
	v_mfma_f32_16x16x32_bf16 v[108:111], v[140:143], v[194:197], v[108:111]
	v_mfma_f32_16x16x32_bf16 v[104:107], v[154:157], v[194:197], v[104:107]
	v_mfma_f32_16x16x32_bf16 v[92:95], v[140:143], v[202:205], v[92:95]
	v_mfma_f32_16x16x32_bf16 v[88:91], v[154:157], v[202:205], v[88:91]
	v_mfma_f32_16x16x32_bf16 v[76:79], v[140:143], v[210:213], v[76:79]
	v_mfma_f32_16x16x32_bf16 v[72:75], v[154:157], v[210:213], v[72:75]
	v_mfma_f32_16x16x32_bf16 v[124:127], v[150:153], v[190:193], v[124:127]
	v_mfma_f32_16x16x32_bf16 v[120:123], v[158:161], v[190:193], v[120:123]
	v_mfma_f32_16x16x32_bf16 v[108:111], v[150:153], v[198:201], v[108:111]
	v_mfma_f32_16x16x32_bf16 v[104:107], v[158:161], v[198:201], v[104:107]
	v_mfma_f32_16x16x32_bf16 v[92:95], v[150:153], v[206:209], v[92:95]
	v_mfma_f32_16x16x32_bf16 v[88:91], v[158:161], v[206:209], v[88:91]
	v_mfma_f32_16x16x32_bf16 v[76:79], v[150:153], v[214:217], v[76:79]
	v_mfma_f32_16x16x32_bf16 v[72:75], v[158:161], v[214:217], v[72:75]
	v_mfma_f32_16x16x32_bf16 v[116:119], v[162:165], v[186:189], v[116:119]
	v_mfma_f32_16x16x32_bf16 v[112:115], v[170:173], v[186:189], v[112:115]
	v_mfma_f32_16x16x32_bf16 v[100:103], v[162:165], v[194:197], v[100:103]
	v_mfma_f32_16x16x32_bf16 v[96:99], v[170:173], v[194:197], v[96:99]
	v_mfma_f32_16x16x32_bf16 v[84:87], v[162:165], v[202:205], v[84:87]
	v_mfma_f32_16x16x32_bf16 v[80:83], v[170:173], v[202:205], v[80:83]
	v_mfma_f32_16x16x32_bf16 v[68:71], v[162:165], v[210:213], v[68:71]
	v_mfma_f32_16x16x32_bf16 v[64:67], v[170:173], v[210:213], v[64:67]
	v_mfma_f32_16x16x32_bf16 v[116:119], v[166:169], v[190:193], v[116:119]
	v_mfma_f32_16x16x32_bf16 v[112:115], v[178:181], v[190:193], v[112:115]
	v_mfma_f32_16x16x32_bf16 v[100:103], v[166:169], v[198:201], v[100:103]
	v_mfma_f32_16x16x32_bf16 v[96:99], v[178:181], v[198:201], v[96:99]
	v_mfma_f32_16x16x32_bf16 v[84:87], v[166:169], v[206:209], v[84:87]
	v_mfma_f32_16x16x32_bf16 v[80:83], v[178:181], v[206:209], v[80:83]
	v_mfma_f32_16x16x32_bf16 v[68:71], v[166:169], v[214:217], v[68:71]
	v_mfma_f32_16x16x32_bf16 v[64:67], v[178:181], v[214:217], v[64:67]
	s_barrier
	s_add_i32 s53, s53, s38
	v_lshl_add_u64 v[144:145], s[26:27], 0, v[130:131]
	s_mov_b32 m0, s53
	ds_read_b128 v[186:189], v149 offset:16384
	ds_read_b128 v[190:193], v149 offset:17408
	ds_read_b128 v[194:197], v149 offset:18432
	ds_read_b128 v[198:201], v149 offset:19456
	ds_read_b128 v[202:205], v149 offset:20480
	ds_read_b128 v[206:209], v149 offset:21504
	ds_read_b128 v[210:213], v149 offset:22528
	ds_read_b128 v[214:217], v149 offset:23552
	global_load_lds_dwordx4 v[144:145], off
	s_add_i32 m0, s53, 0x2000
	s_add_u32 s56, s26, 0x40000
	v_lshl_add_u64 v[174:175], s[26:27], 0, v[134:135]
	s_addc_u32 s57, s27, 0
	s_add_i32 s53, s58, s38
	global_load_lds_dwordx4 v[174:175], off
	v_lshl_add_u64 v[218:219], s[56:57], 0, v[130:131]
	s_mov_b32 m0, s53
	v_lshl_add_u64 v[222:223], s[28:29], 0, v[132:133]
	global_load_lds_dwordx4 v[218:219], off
	v_lshl_add_u64 v[218:219], s[56:57], 0, v[134:135]
	s_add_i32 m0, s53, 0x2000
	s_nop 0
	global_load_lds_dwordx4 v[218:219], off
	v_lshl_add_u64 v[218:219], s[28:29], 0, v[128:129]
	s_mov_b32 m0, s39
	s_nop 0
	global_load_lds_dwordx4 v[218:219], off
	s_mov_b32 m0, s40
	s_nop 0
	global_load_lds_dwordx4 v[222:223], off
	s_waitcnt vmcnt(8)
	s_waitcnt lgkmcnt(0)
	s_barrier
	s_waitcnt lgkmcnt(0)
	v_mfma_f32_16x16x32_bf16 v[60:63], v[140:143], v[186:189], v[60:63]
	v_mfma_f32_16x16x32_bf16 v[56:59], v[154:157], v[186:189], v[56:59]
	v_mfma_f32_16x16x32_bf16 v[44:47], v[140:143], v[194:197], v[44:47]
	v_mfma_f32_16x16x32_bf16 v[40:43], v[154:157], v[194:197], v[40:43]
	v_mfma_f32_16x16x32_bf16 v[28:31], v[140:143], v[202:205], v[28:31]
	v_mfma_f32_16x16x32_bf16 v[24:27], v[154:157], v[202:205], v[24:27]
	v_mfma_f32_16x16x32_bf16 v[12:15], v[140:143], v[210:213], v[12:15]
	v_mfma_f32_16x16x32_bf16 v[8:11], v[154:157], v[210:213], v[8:11]
	v_mfma_f32_16x16x32_bf16 v[60:63], v[150:153], v[190:193], v[60:63]
	v_mfma_f32_16x16x32_bf16 v[56:59], v[158:161], v[190:193], v[56:59]
	v_mfma_f32_16x16x32_bf16 v[44:47], v[150:153], v[198:201], v[44:47]
	v_mfma_f32_16x16x32_bf16 v[40:43], v[158:161], v[198:201], v[40:43]
	v_mfma_f32_16x16x32_bf16 v[28:31], v[150:153], v[206:209], v[28:31]
	v_mfma_f32_16x16x32_bf16 v[24:27], v[158:161], v[206:209], v[24:27]
	v_mfma_f32_16x16x32_bf16 v[12:15], v[150:153], v[214:217], v[12:15]
	v_mfma_f32_16x16x32_bf16 v[8:11], v[158:161], v[214:217], v[8:11]
	v_mfma_f32_16x16x32_bf16 v[52:55], v[162:165], v[186:189], v[52:55]
	v_mfma_f32_16x16x32_bf16 v[48:51], v[170:173], v[186:189], v[48:51]
	v_mfma_f32_16x16x32_bf16 v[36:39], v[162:165], v[194:197], v[36:39]
	v_mfma_f32_16x16x32_bf16 v[32:35], v[170:173], v[194:197], v[32:35]
	v_mfma_f32_16x16x32_bf16 v[20:23], v[162:165], v[202:205], v[20:23]
	v_mfma_f32_16x16x32_bf16 v[16:19], v[170:173], v[202:205], v[16:19]
	v_mfma_f32_16x16x32_bf16 v[4:7], v[162:165], v[210:213], v[4:7]
	v_mfma_f32_16x16x32_bf16 v[0:3], v[170:173], v[210:213], v[0:3]
	v_mfma_f32_16x16x32_bf16 v[52:55], v[166:169], v[190:193], v[52:55]
	v_mfma_f32_16x16x32_bf16 v[48:51], v[178:181], v[190:193], v[48:51]
	v_mfma_f32_16x16x32_bf16 v[36:39], v[166:169], v[198:201], v[36:39]
	v_mfma_f32_16x16x32_bf16 v[32:35], v[178:181], v[198:201], v[32:35]
	v_mfma_f32_16x16x32_bf16 v[20:23], v[166:169], v[206:209], v[20:23]
	v_mfma_f32_16x16x32_bf16 v[16:19], v[178:181], v[206:209], v[16:19]
	v_mfma_f32_16x16x32_bf16 v[4:7], v[166:169], v[214:217], v[4:7]
	v_mfma_f32_16x16x32_bf16 v[0:3], v[178:181], v[214:217], v[0:3]
	s_barrier
	s_add_i32 s53, 0, 0x18000
	s_add_i32 s56, 0, 0x1c000
	v_add_u32_e32 v158, s53, v147
	v_add_u32_e32 v176, s56, v147
	ds_read_b128 v[140:143], v158
	ds_read_b128 v[150:153], v158 offset:1024
	ds_read_b128 v[154:157], v158 offset:2048
	ds_read_b128 v[158:161], v158 offset:3072
	ds_read_b128 v[162:165], v176
	ds_read_b128 v[166:169], v176 offset:1024
	ds_read_b128 v[170:173], v176 offset:2048
	ds_read_b128 v[178:181], v176 offset:3072
	s_add_u32 s28, s28, 0x40000
	s_addc_u32 s29, s29, 0
	s_mov_b32 m0, s41
	v_lshl_add_u64 v[226:227], s[28:29], 0, v[128:129]
	ds_read_b128 v[186:189], v149 offset:32768
	ds_read_b128 v[190:193], v149 offset:33792
	ds_read_b128 v[194:197], v149 offset:34816
	ds_read_b128 v[198:201], v149 offset:35840
	ds_read_b128 v[202:205], v149 offset:36864
	ds_read_b128 v[206:209], v149 offset:37888
	ds_read_b128 v[210:213], v149 offset:38912
	ds_read_b128 v[214:217], v149 offset:39936
	global_load_lds_dwordx4 v[226:227], off
	v_lshl_add_u64 v[226:227], s[28:29], 0, v[132:133]
	s_mov_b32 m0, s44
	s_nop 0
	global_load_lds_dwordx4 v[226:227], off
	s_waitcnt vmcnt(8)
	s_waitcnt lgkmcnt(0)
	s_barrier
	s_waitcnt lgkmcnt(0)
	v_mfma_f32_16x16x32_bf16 v[124:127], v[140:143], v[186:189], v[124:127]
	v_mfma_f32_16x16x32_bf16 v[120:123], v[154:157], v[186:189], v[120:123]
	v_mfma_f32_16x16x32_bf16 v[108:111], v[140:143], v[194:197], v[108:111]
	v_mfma_f32_16x16x32_bf16 v[104:107], v[154:157], v[194:197], v[104:107]
	v_mfma_f32_16x16x32_bf16 v[92:95], v[140:143], v[202:205], v[92:95]
	v_mfma_f32_16x16x32_bf16 v[88:91], v[154:157], v[202:205], v[88:91]
	v_mfma_f32_16x16x32_bf16 v[76:79], v[140:143], v[210:213], v[76:79]
	v_mfma_f32_16x16x32_bf16 v[72:75], v[154:157], v[210:213], v[72:75]
	v_mfma_f32_16x16x32_bf16 v[124:127], v[150:153], v[190:193], v[124:127]
	v_mfma_f32_16x16x32_bf16 v[120:123], v[158:161], v[190:193], v[120:123]
	v_mfma_f32_16x16x32_bf16 v[108:111], v[150:153], v[198:201], v[108:111]
	v_mfma_f32_16x16x32_bf16 v[104:107], v[158:161], v[198:201], v[104:107]
	v_mfma_f32_16x16x32_bf16 v[92:95], v[150:153], v[206:209], v[92:95]
	v_mfma_f32_16x16x32_bf16 v[88:91], v[158:161], v[206:209], v[88:91]
	v_mfma_f32_16x16x32_bf16 v[76:79], v[150:153], v[214:217], v[76:79]
	v_mfma_f32_16x16x32_bf16 v[72:75], v[158:161], v[214:217], v[72:75]
	v_mfma_f32_16x16x32_bf16 v[116:119], v[162:165], v[186:189], v[116:119]
	v_mfma_f32_16x16x32_bf16 v[112:115], v[170:173], v[186:189], v[112:115]
	v_mfma_f32_16x16x32_bf16 v[100:103], v[162:165], v[194:197], v[100:103]
	v_mfma_f32_16x16x32_bf16 v[96:99], v[170:173], v[194:197], v[96:99]
	v_mfma_f32_16x16x32_bf16 v[84:87], v[162:165], v[202:205], v[84:87]
	v_mfma_f32_16x16x32_bf16 v[80:83], v[170:173], v[202:205], v[80:83]
	v_mfma_f32_16x16x32_bf16 v[68:71], v[162:165], v[210:213], v[68:71]
	v_mfma_f32_16x16x32_bf16 v[64:67], v[170:173], v[210:213], v[64:67]
	v_mfma_f32_16x16x32_bf16 v[116:119], v[166:169], v[190:193], v[116:119]
	v_mfma_f32_16x16x32_bf16 v[112:115], v[178:181], v[190:193], v[112:115]
	v_mfma_f32_16x16x32_bf16 v[100:103], v[166:169], v[198:201], v[100:103]
	v_mfma_f32_16x16x32_bf16 v[96:99], v[178:181], v[198:201], v[96:99]
	v_mfma_f32_16x16x32_bf16 v[84:87], v[166:169], v[206:209], v[84:87]
	v_mfma_f32_16x16x32_bf16 v[80:83], v[178:181], v[206:209], v[80:83]
	v_mfma_f32_16x16x32_bf16 v[68:71], v[166:169], v[214:217], v[68:71]
	v_mfma_f32_16x16x32_bf16 v[64:67], v[178:181], v[214:217], v[64:67]
	s_barrier
	s_add_i32 s28, s53, s38
	v_lshl_add_u64 v[144:145], v[144:145], 0, s[72:73]
	s_mov_b32 m0, s28
	ds_read_b128 v[186:189], v149 offset:49152
	ds_read_b128 v[190:193], v149 offset:50176
	ds_read_b128 v[194:197], v149 offset:51200
	ds_read_b128 v[198:201], v149 offset:52224
	ds_read_b128 v[202:205], v149 offset:53248
	ds_read_b128 v[206:209], v149 offset:54272
	ds_read_b128 v[210:213], v149 offset:55296
	ds_read_b128 v[214:217], v149 offset:56320
	global_load_lds_dwordx4 v[144:145], off
	s_add_i32 m0, s28, 0x2000
	s_add_u32 s26, s26, 0x40080
	v_lshl_add_u64 v[144:145], v[174:175], 0, s[72:73]
	s_addc_u32 s27, s27, 0
	s_add_i32 s28, s56, s38
	global_load_lds_dwordx4 v[144:145], off
	v_lshl_add_u64 v[144:145], s[26:27], 0, v[130:131]
	s_mov_b32 m0, s28
	s_nop 0
	global_load_lds_dwordx4 v[144:145], off
	v_lshl_add_u64 v[144:145], s[26:27], 0, v[134:135]
	s_add_i32 m0, s28, 0x2000
	s_nop 0
	global_load_lds_dwordx4 v[144:145], off
	v_lshl_add_u64 v[144:145], v[218:219], 0, s[72:73]
	s_mov_b32 m0, s45
	s_nop 0
	global_load_lds_dwordx4 v[144:145], off
	v_lshl_add_u64 v[144:145], v[222:223], 0, s[72:73]
	s_mov_b32 m0, s46
	s_nop 0
	global_load_lds_dwordx4 v[144:145], off
	s_waitcnt vmcnt(8)
	s_waitcnt lgkmcnt(0)
	s_barrier
	s_waitcnt lgkmcnt(0)
	v_mfma_f32_16x16x32_bf16 v[60:63], v[140:143], v[186:189], v[60:63]
	v_mfma_f32_16x16x32_bf16 v[56:59], v[154:157], v[186:189], v[56:59]
	v_mfma_f32_16x16x32_bf16 v[44:47], v[140:143], v[194:197], v[44:47]
	v_mfma_f32_16x16x32_bf16 v[40:43], v[154:157], v[194:197], v[40:43]
	v_mfma_f32_16x16x32_bf16 v[28:31], v[140:143], v[202:205], v[28:31]
	v_mfma_f32_16x16x32_bf16 v[24:27], v[154:157], v[202:205], v[24:27]
	v_mfma_f32_16x16x32_bf16 v[12:15], v[140:143], v[210:213], v[12:15]
	v_mfma_f32_16x16x32_bf16 v[8:11], v[154:157], v[210:213], v[8:11]
	v_mfma_f32_16x16x32_bf16 v[60:63], v[150:153], v[190:193], v[60:63]
	v_mfma_f32_16x16x32_bf16 v[56:59], v[158:161], v[190:193], v[56:59]
	v_mfma_f32_16x16x32_bf16 v[44:47], v[150:153], v[198:201], v[44:47]
	v_mfma_f32_16x16x32_bf16 v[40:43], v[158:161], v[198:201], v[40:43]
	v_mfma_f32_16x16x32_bf16 v[28:31], v[150:153], v[206:209], v[28:31]
	v_mfma_f32_16x16x32_bf16 v[24:27], v[158:161], v[206:209], v[24:27]
	v_mfma_f32_16x16x32_bf16 v[12:15], v[150:153], v[214:217], v[12:15]
	v_mfma_f32_16x16x32_bf16 v[8:11], v[158:161], v[214:217], v[8:11]
	v_mfma_f32_16x16x32_bf16 v[52:55], v[162:165], v[186:189], v[52:55]
	v_mfma_f32_16x16x32_bf16 v[48:51], v[170:173], v[186:189], v[48:51]
	v_mfma_f32_16x16x32_bf16 v[36:39], v[162:165], v[194:197], v[36:39]
	v_mfma_f32_16x16x32_bf16 v[32:35], v[170:173], v[194:197], v[32:35]
	v_mfma_f32_16x16x32_bf16 v[20:23], v[162:165], v[202:205], v[20:23]
	v_mfma_f32_16x16x32_bf16 v[16:19], v[170:173], v[202:205], v[16:19]
	v_mfma_f32_16x16x32_bf16 v[4:7], v[162:165], v[210:213], v[4:7]
	v_mfma_f32_16x16x32_bf16 v[0:3], v[170:173], v[210:213], v[0:3]
	v_mfma_f32_16x16x32_bf16 v[52:55], v[166:169], v[190:193], v[52:55]
	v_mfma_f32_16x16x32_bf16 v[48:51], v[178:181], v[190:193], v[48:51]
	v_mfma_f32_16x16x32_bf16 v[36:39], v[166:169], v[198:201], v[36:39]
	v_mfma_f32_16x16x32_bf16 v[32:35], v[178:181], v[198:201], v[32:35]
	v_mfma_f32_16x16x32_bf16 v[20:23], v[166:169], v[206:209], v[20:23]
	v_mfma_f32_16x16x32_bf16 v[16:19], v[178:181], v[206:209], v[16:19]
	v_mfma_f32_16x16x32_bf16 v[4:7], v[166:169], v[214:217], v[4:7]
	v_mfma_f32_16x16x32_bf16 v[0:3], v[178:181], v[214:217], v[0:3]
	s_barrier
	s_add_i32 s50, s50, 2
	s_add_u32 s42, s42, 0x100
	s_addc_u32 s43, s43, 0
	s_add_u32 s24, s24, 0x100
	s_addc_u32 s25, s25, 0
	s_cmp_gt_u32 s50, 13
	s_cbranch_scc0 .LBB0_588
	s_and_b64 vcc, exec, s[14:15]
	s_cbranch_vccz .LBB0_591
	s_barrier

.LBB0_708:
	s_add_u32 s22, s20, 0xfffc0080
	s_addc_u32 s23, s21, -1
	s_add_i32 s50, 0, 0x10000
	s_cmp_eq_u32 s49, 12
	s_cselect_b32 s25, s15, s23
	s_cselect_b32 s24, s44, s22
	s_cselect_b32 s23, s13, s48
	s_cselect_b32 s22, s45, s46
	s_add_i32 s56, 0, 0x14000
	v_add_u32_e32 v154, s50, v139
	v_add_u32_e32 v170, s56, v139
	ds_read_b128 v[142:145], v154
	ds_read_b128 v[146:149], v154 offset:1024
	ds_read_b128 v[150:153], v154 offset:2048
	ds_read_b128 v[154:157], v154 offset:3072
	ds_read_b128 v[158:161], v170
	ds_read_b128 v[162:165], v170 offset:1024
	ds_read_b128 v[166:169], v170 offset:2048
	ds_read_b128 v[170:173], v170 offset:3072
	v_lshl_add_u64 v[174:175], s[20:21], 0, v[136:137]
	s_add_i32 m0, s37, 0xc000
	ds_read_b128 v[178:181], v141
	ds_read_b128 v[186:189], v141 offset:1024
	ds_read_b128 v[190:193], v141 offset:2048
	ds_read_b128 v[194:197], v141 offset:3072
	ds_read_b128 v[198:201], v141 offset:4096
	ds_read_b128 v[202:205], v141 offset:5120
	ds_read_b128 v[206:209], v141 offset:6144
	ds_read_b128 v[210:213], v141 offset:7168
	global_load_lds_dwordx4 v[174:175], off
	v_lshl_add_u64 v[174:175], s[20:21], 0, v[134:135]
	s_add_i32 m0, s37, 0xe000
	s_nop 0
	global_load_lds_dwordx4 v[174:175], off
	s_waitcnt vmcnt(8)
	s_waitcnt lgkmcnt(0)
	s_barrier
	s_waitcnt lgkmcnt(0)
	v_mfma_f32_16x16x32_bf16 v[124:127], v[142:145], v[178:181], v[124:127]
	v_mfma_f32_16x16x32_bf16 v[120:123], v[150:153], v[178:181], v[120:123]
	v_mfma_f32_16x16x32_bf16 v[116:119], v[142:145], v[190:193], v[116:119]
	v_mfma_f32_16x16x32_bf16 v[112:115], v[150:153], v[190:193], v[112:115]
	v_mfma_f32_16x16x32_bf16 v[100:103], v[142:145], v[198:201], v[100:103]
	v_mfma_f32_16x16x32_bf16 v[96:99], v[150:153], v[198:201], v[96:99]
	v_mfma_f32_16x16x32_bf16 v[84:87], v[142:145], v[206:209], v[84:87]
	v_mfma_f32_16x16x32_bf16 v[80:83], v[150:153], v[206:209], v[80:83]
	v_mfma_f32_16x16x32_bf16 v[124:127], v[146:149], v[186:189], v[124:127]
	v_mfma_f32_16x16x32_bf16 v[120:123], v[154:157], v[186:189], v[120:123]
	v_mfma_f32_16x16x32_bf16 v[116:119], v[146:149], v[194:197], v[116:119]
	v_mfma_f32_16x16x32_bf16 v[112:115], v[154:157], v[194:197], v[112:115]
	v_mfma_f32_16x16x32_bf16 v[100:103], v[146:149], v[202:205], v[100:103]
	v_mfma_f32_16x16x32_bf16 v[96:99], v[154:157], v[202:205], v[96:99]
	v_mfma_f32_16x16x32_bf16 v[84:87], v[146:149], v[210:213], v[84:87]
	v_mfma_f32_16x16x32_bf16 v[80:83], v[154:157], v[210:213], v[80:83]
	v_mfma_f32_16x16x32_bf16 v[108:111], v[158:161], v[178:181], v[108:111]
	v_mfma_f32_16x16x32_bf16 v[104:107], v[166:169], v[178:181], v[104:107]
	v_mfma_f32_16x16x32_bf16 v[92:95], v[158:161], v[190:193], v[92:95]
	v_mfma_f32_16x16x32_bf16 v[88:91], v[166:169], v[190:193], v[88:91]
	v_mfma_f32_16x16x32_bf16 v[76:79], v[158:161], v[198:201], v[76:79]
	v_mfma_f32_16x16x32_bf16 v[72:75], v[166:169], v[198:201], v[72:75]
	v_mfma_f32_16x16x32_bf16 v[68:71], v[158:161], v[206:209], v[68:71]
	v_mfma_f32_16x16x32_bf16 v[64:67], v[166:169], v[206:209], v[64:67]
	v_mfma_f32_16x16x32_bf16 v[108:111], v[162:165], v[186:189], v[108:111]
	v_mfma_f32_16x16x32_bf16 v[104:107], v[170:173], v[186:189], v[104:107]
	v_mfma_f32_16x16x32_bf16 v[92:95], v[162:165], v[194:197], v[92:95]
	v_mfma_f32_16x16x32_bf16 v[88:91], v[170:173], v[194:197], v[88:91]
	v_mfma_f32_16x16x32_bf16 v[76:79], v[162:165], v[202:205], v[76:79]
	v_mfma_f32_16x16x32_bf16 v[72:75], v[170:173], v[202:205], v[72:75]
	v_mfma_f32_16x16x32_bf16 v[68:71], v[162:165], v[210:213], v[68:71]
	v_mfma_f32_16x16x32_bf16 v[64:67], v[170:173], v[210:213], v[64:67]
	s_barrier
	s_add_i32 s50, s50, s36
	v_lshl_add_u64 v[174:175], s[22:23], 0, v[176:177]
	s_mov_b32 m0, s50
	ds_read_b128 v[178:181], v141 offset:16384
	ds_read_b128 v[186:189], v141 offset:17408
	ds_read_b128 v[190:193], v141 offset:18432
	ds_read_b128 v[194:197], v141 offset:19456
	ds_read_b128 v[198:201], v141 offset:20480
	ds_read_b128 v[202:205], v141 offset:21504
	ds_read_b128 v[206:209], v141 offset:22528
	ds_read_b128 v[210:213], v141 offset:23552
	global_load_lds_dwordx4 v[174:175], off
	s_add_i32 m0, s50, 0x2000
	s_add_u32 s52, s22, 0x40000
	v_lshl_add_u64 v[214:215], s[22:23], 0, v[132:133]
	s_addc_u32 s53, s23, 0
	s_add_i32 s50, s56, s36
	global_load_lds_dwordx4 v[214:215], off
	v_lshl_add_u64 v[216:217], s[52:53], 0, v[176:177]
	s_mov_b32 m0, s50
	v_lshl_add_u64 v[218:219], s[24:25], 0, v[130:131]
	global_load_lds_dwordx4 v[216:217], off
	v_lshl_add_u64 v[216:217], s[52:53], 0, v[132:133]
	s_add_i32 m0, s50, 0x2000
	s_nop 0
	global_load_lds_dwordx4 v[216:217], off
	v_lshl_add_u64 v[216:217], s[24:25], 0, v[128:129]
	s_mov_b32 m0, s37
	s_nop 0
	global_load_lds_dwordx4 v[216:217], off
	s_mov_b32 m0, s38
	s_nop 0
	global_load_lds_dwordx4 v[218:219], off
	s_waitcnt vmcnt(8)
	s_waitcnt lgkmcnt(0)
	s_barrier
	s_waitcnt lgkmcnt(0)
	v_mfma_f32_16x16x32_bf16 v[60:63], v[142:145], v[178:181], v[60:63]
	v_mfma_f32_16x16x32_bf16 v[56:59], v[150:153], v[178:181], v[56:59]
	v_mfma_f32_16x16x32_bf16 v[52:55], v[142:145], v[190:193], v[52:55]
	v_mfma_f32_16x16x32_bf16 v[48:51], v[150:153], v[190:193], v[48:51]
	v_mfma_f32_16x16x32_bf16 v[36:39], v[142:145], v[198:201], v[36:39]
	v_mfma_f32_16x16x32_bf16 v[32:35], v[150:153], v[198:201], v[32:35]
	v_mfma_f32_16x16x32_bf16 v[20:23], v[142:145], v[206:209], v[20:23]
	v_mfma_f32_16x16x32_bf16 v[16:19], v[150:153], v[206:209], v[16:19]
	v_mfma_f32_16x16x32_bf16 v[60:63], v[146:149], v[186:189], v[60:63]
	v_mfma_f32_16x16x32_bf16 v[56:59], v[154:157], v[186:189], v[56:59]
	v_mfma_f32_16x16x32_bf16 v[52:55], v[146:149], v[194:197], v[52:55]
	v_mfma_f32_16x16x32_bf16 v[48:51], v[154:157], v[194:197], v[48:51]
	v_mfma_f32_16x16x32_bf16 v[36:39], v[146:149], v[202:205], v[36:39]
	v_mfma_f32_16x16x32_bf16 v[32:35], v[154:157], v[202:205], v[32:35]
	v_mfma_f32_16x16x32_bf16 v[20:23], v[146:149], v[210:213], v[20:23]
	v_mfma_f32_16x16x32_bf16 v[16:19], v[154:157], v[210:213], v[16:19]
	v_mfma_f32_16x16x32_bf16 v[44:47], v[158:161], v[178:181], v[44:47]
	v_mfma_f32_16x16x32_bf16 v[40:43], v[166:169], v[178:181], v[40:43]
	v_mfma_f32_16x16x32_bf16 v[28:31], v[158:161], v[190:193], v[28:31]
	v_mfma_f32_16x16x32_bf16 v[24:27], v[166:169], v[190:193], v[24:27]
	v_mfma_f32_16x16x32_bf16 v[12:15], v[158:161], v[198:201], v[12:15]
	v_mfma_f32_16x16x32_bf16 v[8:11], v[166:169], v[198:201], v[8:11]
	v_mfma_f32_16x16x32_bf16 v[4:7], v[158:161], v[206:209], v[4:7]
	v_mfma_f32_16x16x32_bf16 v[0:3], v[166:169], v[206:209], v[0:3]
	v_mfma_f32_16x16x32_bf16 v[44:47], v[162:165], v[186:189], v[44:47]
	v_mfma_f32_16x16x32_bf16 v[40:43], v[170:173], v[186:189], v[40:43]
	v_mfma_f32_16x16x32_bf16 v[28:31], v[162:165], v[194:197], v[28:31]
	v_mfma_f32_16x16x32_bf16 v[24:27], v[170:173], v[194:197], v[24:27]
	v_mfma_f32_16x16x32_bf16 v[12:15], v[162:165], v[202:205], v[12:15]
	v_mfma_f32_16x16x32_bf16 v[8:11], v[170:173], v[202:205], v[8:11]
	v_mfma_f32_16x16x32_bf16 v[4:7], v[162:165], v[210:213], v[4:7]
	v_mfma_f32_16x16x32_bf16 v[0:3], v[170:173], v[210:213], v[0:3]
	s_barrier
	s_add_i32 s50, 0, 0x18000
	s_add_i32 s52, 0, 0x1c000
	v_add_u32_e32 v154, s50, v139
	v_add_u32_e32 v170, s52, v139
	ds_read_b128 v[142:145], v154
	ds_read_b128 v[146:149], v154 offset:1024
	ds_read_b128 v[150:153], v154 offset:2048
	ds_read_b128 v[154:157], v154 offset:3072
	ds_read_b128 v[158:161], v170
	ds_read_b128 v[162:165], v170 offset:1024
	ds_read_b128 v[166:169], v170 offset:2048
	ds_read_b128 v[170:173], v170 offset:3072
	s_add_u32 s24, s24, 0x40000
	s_addc_u32 s25, s25, 0
	s_mov_b32 m0, s39
	v_lshl_add_u64 v[222:223], s[24:25], 0, v[128:129]
	ds_read_b128 v[178:181], v141 offset:32768
	ds_read_b128 v[186:189], v141 offset:33792
	ds_read_b128 v[190:193], v141 offset:34816
	ds_read_b128 v[194:197], v141 offset:35840
	ds_read_b128 v[198:201], v141 offset:36864
	ds_read_b128 v[202:205], v141 offset:37888
	ds_read_b128 v[206:209], v141 offset:38912
	ds_read_b128 v[210:213], v141 offset:39936
	global_load_lds_dwordx4 v[222:223], off
	v_lshl_add_u64 v[222:223], s[24:25], 0, v[130:131]
	s_mov_b32 m0, s40
	s_nop 0
	global_load_lds_dwordx4 v[222:223], off
	s_waitcnt vmcnt(8)
	s_waitcnt lgkmcnt(0)
	s_barrier
	s_waitcnt lgkmcnt(0)
	v_mfma_f32_16x16x32_bf16 v[124:127], v[142:145], v[178:181], v[124:127]
	v_mfma_f32_16x16x32_bf16 v[120:123], v[150:153], v[178:181], v[120:123]
	v_mfma_f32_16x16x32_bf16 v[116:119], v[142:145], v[190:193], v[116:119]
	v_mfma_f32_16x16x32_bf16 v[112:115], v[150:153], v[190:193], v[112:115]
	v_mfma_f32_16x16x32_bf16 v[100:103], v[142:145], v[198:201], v[100:103]
	v_mfma_f32_16x16x32_bf16 v[96:99], v[150:153], v[198:201], v[96:99]
	v_mfma_f32_16x16x32_bf16 v[84:87], v[142:145], v[206:209], v[84:87]
	v_mfma_f32_16x16x32_bf16 v[80:83], v[150:153], v[206:209], v[80:83]
	v_mfma_f32_16x16x32_bf16 v[124:127], v[146:149], v[186:189], v[124:127]
	v_mfma_f32_16x16x32_bf16 v[120:123], v[154:157], v[186:189], v[120:123]
	v_mfma_f32_16x16x32_bf16 v[116:119], v[146:149], v[194:197], v[116:119]
	v_mfma_f32_16x16x32_bf16 v[112:115], v[154:157], v[194:197], v[112:115]
	v_mfma_f32_16x16x32_bf16 v[100:103], v[146:149], v[202:205], v[100:103]
	v_mfma_f32_16x16x32_bf16 v[96:99], v[154:157], v[202:205], v[96:99]
	v_mfma_f32_16x16x32_bf16 v[84:87], v[146:149], v[210:213], v[84:87]
	v_mfma_f32_16x16x32_bf16 v[80:83], v[154:157], v[210:213], v[80:83]
	v_mfma_f32_16x16x32_bf16 v[108:111], v[158:161], v[178:181], v[108:111]
	v_mfma_f32_16x16x32_bf16 v[104:107], v[166:169], v[178:181], v[104:107]
	v_mfma_f32_16x16x32_bf16 v[92:95], v[158:161], v[190:193], v[92:95]
	v_mfma_f32_16x16x32_bf16 v[88:91], v[166:169], v[190:193], v[88:91]
	v_mfma_f32_16x16x32_bf16 v[76:79], v[158:161], v[198:201], v[76:79]
	v_mfma_f32_16x16x32_bf16 v[72:75], v[166:169], v[198:201], v[72:75]
	v_mfma_f32_16x16x32_bf16 v[68:71], v[158:161], v[206:209], v[68:71]
	v_mfma_f32_16x16x32_bf16 v[64:67], v[166:169], v[206:209], v[64:67]
	v_mfma_f32_16x16x32_bf16 v[108:111], v[162:165], v[186:189], v[108:111]
	v_mfma_f32_16x16x32_bf16 v[104:107], v[170:173], v[186:189], v[104:107]
	v_mfma_f32_16x16x32_bf16 v[92:95], v[162:165], v[194:197], v[92:95]
	v_mfma_f32_16x16x32_bf16 v[88:91], v[170:173], v[194:197], v[88:91]
	v_mfma_f32_16x16x32_bf16 v[76:79], v[162:165], v[202:205], v[76:79]
	v_mfma_f32_16x16x32_bf16 v[72:75], v[170:173], v[202:205], v[72:75]
	v_mfma_f32_16x16x32_bf16 v[68:71], v[162:165], v[210:213], v[68:71]
	v_mfma_f32_16x16x32_bf16 v[64:67], v[170:173], v[210:213], v[64:67]
	s_barrier
	s_add_i32 s24, s50, s36
	v_lshl_add_u64 v[174:175], v[174:175], 0, s[72:73]
	s_mov_b32 m0, s24
	ds_read_b128 v[178:181], v141 offset:49152
	ds_read_b128 v[186:189], v141 offset:50176
	ds_read_b128 v[190:193], v141 offset:51200
	ds_read_b128 v[194:197], v141 offset:52224
	ds_read_b128 v[198:201], v141 offset:53248
	ds_read_b128 v[202:205], v141 offset:54272
	ds_read_b128 v[206:209], v141 offset:55296
	ds_read_b128 v[210:213], v141 offset:56320
	global_load_lds_dwordx4 v[174:175], off
	s_add_i32 m0, s24, 0x2000
	s_add_u32 s22, s22, 0x40080
	v_lshl_add_u64 v[174:175], v[214:215], 0, s[72:73]
	s_addc_u32 s23, s23, 0
	s_add_i32 s24, s52, s36
	global_load_lds_dwordx4 v[174:175], off
	v_lshl_add_u64 v[174:175], s[22:23], 0, v[176:177]
	s_mov_b32 m0, s24
	s_nop 0
	global_load_lds_dwordx4 v[174:175], off
	v_lshl_add_u64 v[174:175], s[22:23], 0, v[132:133]
	s_add_i32 m0, s24, 0x2000
	s_nop 0
	global_load_lds_dwordx4 v[174:175], off
	v_lshl_add_u64 v[174:175], v[216:217], 0, s[72:73]
	s_mov_b32 m0, s41
	s_nop 0
	global_load_lds_dwordx4 v[174:175], off
	v_lshl_add_u64 v[174:175], v[218:219], 0, s[72:73]
	s_mov_b32 m0, s42
	s_nop 0
	global_load_lds_dwordx4 v[174:175], off
	s_waitcnt vmcnt(8)
	s_waitcnt lgkmcnt(0)
	s_barrier
	s_waitcnt lgkmcnt(0)
	v_mfma_f32_16x16x32_bf16 v[60:63], v[142:145], v[178:181], v[60:63]
	v_mfma_f32_16x16x32_bf16 v[56:59], v[150:153], v[178:181], v[56:59]
	v_mfma_f32_16x16x32_bf16 v[52:55], v[142:145], v[190:193], v[52:55]
	v_mfma_f32_16x16x32_bf16 v[48:51], v[150:153], v[190:193], v[48:51]
	v_mfma_f32_16x16x32_bf16 v[36:39], v[142:145], v[198:201], v[36:39]
	v_mfma_f32_16x16x32_bf16 v[32:35], v[150:153], v[198:201], v[32:35]
	v_mfma_f32_16x16x32_bf16 v[20:23], v[142:145], v[206:209], v[20:23]
	v_mfma_f32_16x16x32_bf16 v[16:19], v[150:153], v[206:209], v[16:19]
	v_mfma_f32_16x16x32_bf16 v[60:63], v[146:149], v[186:189], v[60:63]
	v_mfma_f32_16x16x32_bf16 v[56:59], v[154:157], v[186:189], v[56:59]
	v_mfma_f32_16x16x32_bf16 v[52:55], v[146:149], v[194:197], v[52:55]
	v_mfma_f32_16x16x32_bf16 v[48:51], v[154:157], v[194:197], v[48:51]
	v_mfma_f32_16x16x32_bf16 v[36:39], v[146:149], v[202:205], v[36:39]
	v_mfma_f32_16x16x32_bf16 v[32:35], v[154:157], v[202:205], v[32:35]
	v_mfma_f32_16x16x32_bf16 v[20:23], v[146:149], v[210:213], v[20:23]
	v_mfma_f32_16x16x32_bf16 v[16:19], v[154:157], v[210:213], v[16:19]
	v_mfma_f32_16x16x32_bf16 v[44:47], v[158:161], v[178:181], v[44:47]
	v_mfma_f32_16x16x32_bf16 v[40:43], v[166:169], v[178:181], v[40:43]
	v_mfma_f32_16x16x32_bf16 v[28:31], v[158:161], v[190:193], v[28:31]
	v_mfma_f32_16x16x32_bf16 v[24:27], v[166:169], v[190:193], v[24:27]
	v_mfma_f32_16x16x32_bf16 v[12:15], v[158:161], v[198:201], v[12:15]
	v_mfma_f32_16x16x32_bf16 v[8:11], v[166:169], v[198:201], v[8:11]
	v_mfma_f32_16x16x32_bf16 v[4:7], v[158:161], v[206:209], v[4:7]
	v_mfma_f32_16x16x32_bf16 v[0:3], v[166:169], v[206:209], v[0:3]
	v_mfma_f32_16x16x32_bf16 v[44:47], v[162:165], v[186:189], v[44:47]
	v_mfma_f32_16x16x32_bf16 v[40:43], v[170:173], v[186:189], v[40:43]
	v_mfma_f32_16x16x32_bf16 v[28:31], v[162:165], v[194:197], v[28:31]
	v_mfma_f32_16x16x32_bf16 v[24:27], v[170:173], v[194:197], v[24:27]
	v_mfma_f32_16x16x32_bf16 v[12:15], v[162:165], v[202:205], v[12:15]
	v_mfma_f32_16x16x32_bf16 v[8:11], v[170:173], v[202:205], v[8:11]
	v_mfma_f32_16x16x32_bf16 v[4:7], v[162:165], v[210:213], v[4:7]
	v_mfma_f32_16x16x32_bf16 v[0:3], v[170:173], v[210:213], v[0:3]
	s_barrier
	s_add_i32 s49, s49, 2
	s_add_u32 s46, s46, 0x100
	s_addc_u32 s48, s48, 0
	s_add_u32 s20, s20, 0x100
	s_addc_u32 s21, s21, 0
	s_cmp_gt_u32 s49, 13
	s_cbranch_scc0 .LBB0_708
	s_and_b64 vcc, exec, s[6:7]
	s_cbranch_vccz .LBB0_711
	s_barrier

.LBB0_732:
	s_add_u32 s22, s20, 0xfffc0080
	s_addc_u32 s23, s21, -1
	s_add_i32 s50, 0, 0x10000
	s_cmp_eq_u32 s49, 12
	s_cselect_b32 s25, s15, s23
	s_cselect_b32 s24, s44, s22
	s_cselect_b32 s23, s13, s48
	s_cselect_b32 s22, s45, s46
	s_add_i32 s56, 0, 0x14000
	v_add_u32_e32 v154, s50, v139
	v_add_u32_e32 v170, s56, v139
	ds_read_b128 v[142:145], v154
	ds_read_b128 v[146:149], v154 offset:1024
	ds_read_b128 v[150:153], v154 offset:2048
	ds_read_b128 v[154:157], v154 offset:3072
	ds_read_b128 v[158:161], v170
	ds_read_b128 v[162:165], v170 offset:1024
	ds_read_b128 v[166:169], v170 offset:2048
	ds_read_b128 v[170:173], v170 offset:3072
	v_lshl_add_u64 v[174:175], s[20:21], 0, v[136:137]
	s_add_i32 m0, s36, 0xc000
	ds_read_b128 v[178:181], v141
	ds_read_b128 v[186:189], v141 offset:1024
	ds_read_b128 v[190:193], v141 offset:2048
	ds_read_b128 v[194:197], v141 offset:3072
	ds_read_b128 v[198:201], v141 offset:4096
	ds_read_b128 v[202:205], v141 offset:5120
	ds_read_b128 v[206:209], v141 offset:6144
	ds_read_b128 v[210:213], v141 offset:7168
	global_load_lds_dwordx4 v[174:175], off
	v_lshl_add_u64 v[174:175], s[20:21], 0, v[134:135]
	s_add_i32 m0, s36, 0xe000
	s_nop 0
	global_load_lds_dwordx4 v[174:175], off
	s_waitcnt vmcnt(8)
	s_waitcnt lgkmcnt(0)
	s_barrier
	s_waitcnt lgkmcnt(0)
	v_mfma_f32_16x16x32_bf16 v[124:127], v[142:145], v[178:181], v[124:127]
	v_mfma_f32_16x16x32_bf16 v[120:123], v[150:153], v[178:181], v[120:123]
	v_mfma_f32_16x16x32_bf16 v[116:119], v[142:145], v[190:193], v[116:119]
	v_mfma_f32_16x16x32_bf16 v[112:115], v[150:153], v[190:193], v[112:115]
	v_mfma_f32_16x16x32_bf16 v[100:103], v[142:145], v[198:201], v[100:103]
	v_mfma_f32_16x16x32_bf16 v[96:99], v[150:153], v[198:201], v[96:99]
	v_mfma_f32_16x16x32_bf16 v[84:87], v[142:145], v[206:209], v[84:87]
	v_mfma_f32_16x16x32_bf16 v[80:83], v[150:153], v[206:209], v[80:83]
	v_mfma_f32_16x16x32_bf16 v[124:127], v[146:149], v[186:189], v[124:127]
	v_mfma_f32_16x16x32_bf16 v[120:123], v[154:157], v[186:189], v[120:123]
	v_mfma_f32_16x16x32_bf16 v[116:119], v[146:149], v[194:197], v[116:119]
	v_mfma_f32_16x16x32_bf16 v[112:115], v[154:157], v[194:197], v[112:115]
	v_mfma_f32_16x16x32_bf16 v[100:103], v[146:149], v[202:205], v[100:103]
	v_mfma_f32_16x16x32_bf16 v[96:99], v[154:157], v[202:205], v[96:99]
	v_mfma_f32_16x16x32_bf16 v[84:87], v[146:149], v[210:213], v[84:87]
	v_mfma_f32_16x16x32_bf16 v[80:83], v[154:157], v[210:213], v[80:83]
	v_mfma_f32_16x16x32_bf16 v[108:111], v[158:161], v[178:181], v[108:111]
	v_mfma_f32_16x16x32_bf16 v[104:107], v[166:169], v[178:181], v[104:107]
	v_mfma_f32_16x16x32_bf16 v[92:95], v[158:161], v[190:193], v[92:95]
	v_mfma_f32_16x16x32_bf16 v[88:91], v[166:169], v[190:193], v[88:91]
	v_mfma_f32_16x16x32_bf16 v[76:79], v[158:161], v[198:201], v[76:79]
	v_mfma_f32_16x16x32_bf16 v[72:75], v[166:169], v[198:201], v[72:75]
	v_mfma_f32_16x16x32_bf16 v[68:71], v[158:161], v[206:209], v[68:71]
	v_mfma_f32_16x16x32_bf16 v[64:67], v[166:169], v[206:209], v[64:67]
	v_mfma_f32_16x16x32_bf16 v[108:111], v[162:165], v[186:189], v[108:111]
	v_mfma_f32_16x16x32_bf16 v[104:107], v[170:173], v[186:189], v[104:107]
	v_mfma_f32_16x16x32_bf16 v[92:95], v[162:165], v[194:197], v[92:95]
	v_mfma_f32_16x16x32_bf16 v[88:91], v[170:173], v[194:197], v[88:91]
	v_mfma_f32_16x16x32_bf16 v[76:79], v[162:165], v[202:205], v[76:79]
	v_mfma_f32_16x16x32_bf16 v[72:75], v[170:173], v[202:205], v[72:75]
	v_mfma_f32_16x16x32_bf16 v[68:71], v[162:165], v[210:213], v[68:71]
	v_mfma_f32_16x16x32_bf16 v[64:67], v[170:173], v[210:213], v[64:67]
	s_barrier
	s_add_i32 s50, s50, s35
	v_lshl_add_u64 v[174:175], s[22:23], 0, v[176:177]
	s_mov_b32 m0, s50
	ds_read_b128 v[178:181], v141 offset:16384
	ds_read_b128 v[186:189], v141 offset:17408
	ds_read_b128 v[190:193], v141 offset:18432
	ds_read_b128 v[194:197], v141 offset:19456
	ds_read_b128 v[198:201], v141 offset:20480
	ds_read_b128 v[202:205], v141 offset:21504
	ds_read_b128 v[206:209], v141 offset:22528
	ds_read_b128 v[210:213], v141 offset:23552
	global_load_lds_dwordx4 v[174:175], off
	s_add_i32 m0, s50, 0x2000
	s_add_u32 s52, s22, 0x40000
	v_lshl_add_u64 v[214:215], s[22:23], 0, v[132:133]
	s_addc_u32 s53, s23, 0
	s_add_i32 s50, s56, s35
	global_load_lds_dwordx4 v[214:215], off
	v_lshl_add_u64 v[216:217], s[52:53], 0, v[176:177]
	s_mov_b32 m0, s50
	v_lshl_add_u64 v[218:219], s[24:25], 0, v[130:131]
	global_load_lds_dwordx4 v[216:217], off
	v_lshl_add_u64 v[216:217], s[52:53], 0, v[132:133]
	s_add_i32 m0, s50, 0x2000
	s_nop 0
	global_load_lds_dwordx4 v[216:217], off
	v_lshl_add_u64 v[216:217], s[24:25], 0, v[128:129]
	s_mov_b32 m0, s36
	s_nop 0
	global_load_lds_dwordx4 v[216:217], off
	s_mov_b32 m0, s37
	s_nop 0
	global_load_lds_dwordx4 v[218:219], off
	s_waitcnt vmcnt(8)
	s_waitcnt lgkmcnt(0)
	s_barrier
	s_waitcnt lgkmcnt(0)
	v_mfma_f32_16x16x32_bf16 v[60:63], v[142:145], v[178:181], v[60:63]
	v_mfma_f32_16x16x32_bf16 v[56:59], v[150:153], v[178:181], v[56:59]
	v_mfma_f32_16x16x32_bf16 v[52:55], v[142:145], v[190:193], v[52:55]
	v_mfma_f32_16x16x32_bf16 v[48:51], v[150:153], v[190:193], v[48:51]
	v_mfma_f32_16x16x32_bf16 v[36:39], v[142:145], v[198:201], v[36:39]
	v_mfma_f32_16x16x32_bf16 v[32:35], v[150:153], v[198:201], v[32:35]
	v_mfma_f32_16x16x32_bf16 v[20:23], v[142:145], v[206:209], v[20:23]
	v_mfma_f32_16x16x32_bf16 v[16:19], v[150:153], v[206:209], v[16:19]
	v_mfma_f32_16x16x32_bf16 v[60:63], v[146:149], v[186:189], v[60:63]
	v_mfma_f32_16x16x32_bf16 v[56:59], v[154:157], v[186:189], v[56:59]
	v_mfma_f32_16x16x32_bf16 v[52:55], v[146:149], v[194:197], v[52:55]
	v_mfma_f32_16x16x32_bf16 v[48:51], v[154:157], v[194:197], v[48:51]
	v_mfma_f32_16x16x32_bf16 v[36:39], v[146:149], v[202:205], v[36:39]
	v_mfma_f32_16x16x32_bf16 v[32:35], v[154:157], v[202:205], v[32:35]
	v_mfma_f32_16x16x32_bf16 v[20:23], v[146:149], v[210:213], v[20:23]
	v_mfma_f32_16x16x32_bf16 v[16:19], v[154:157], v[210:213], v[16:19]
	v_mfma_f32_16x16x32_bf16 v[44:47], v[158:161], v[178:181], v[44:47]
	v_mfma_f32_16x16x32_bf16 v[40:43], v[166:169], v[178:181], v[40:43]
	v_mfma_f32_16x16x32_bf16 v[28:31], v[158:161], v[190:193], v[28:31]
	v_mfma_f32_16x16x32_bf16 v[24:27], v[166:169], v[190:193], v[24:27]
	v_mfma_f32_16x16x32_bf16 v[12:15], v[158:161], v[198:201], v[12:15]
	v_mfma_f32_16x16x32_bf16 v[8:11], v[166:169], v[198:201], v[8:11]
	v_mfma_f32_16x16x32_bf16 v[4:7], v[158:161], v[206:209], v[4:7]
	v_mfma_f32_16x16x32_bf16 v[0:3], v[166:169], v[206:209], v[0:3]
	v_mfma_f32_16x16x32_bf16 v[44:47], v[162:165], v[186:189], v[44:47]
	v_mfma_f32_16x16x32_bf16 v[40:43], v[170:173], v[186:189], v[40:43]
	v_mfma_f32_16x16x32_bf16 v[28:31], v[162:165], v[194:197], v[28:31]
	v_mfma_f32_16x16x32_bf16 v[24:27], v[170:173], v[194:197], v[24:27]
	v_mfma_f32_16x16x32_bf16 v[12:15], v[162:165], v[202:205], v[12:15]
	v_mfma_f32_16x16x32_bf16 v[8:11], v[170:173], v[202:205], v[8:11]
	v_mfma_f32_16x16x32_bf16 v[4:7], v[162:165], v[210:213], v[4:7]
	v_mfma_f32_16x16x32_bf16 v[0:3], v[170:173], v[210:213], v[0:3]
	s_barrier
	s_add_i32 s50, 0, 0x18000
	s_add_i32 s52, 0, 0x1c000
	v_add_u32_e32 v154, s50, v139
	v_add_u32_e32 v170, s52, v139
	ds_read_b128 v[142:145], v154
	ds_read_b128 v[146:149], v154 offset:1024
	ds_read_b128 v[150:153], v154 offset:2048
	ds_read_b128 v[154:157], v154 offset:3072
	ds_read_b128 v[158:161], v170
	ds_read_b128 v[162:165], v170 offset:1024
	ds_read_b128 v[166:169], v170 offset:2048
	ds_read_b128 v[170:173], v170 offset:3072
	s_add_u32 s24, s24, 0x40000
	s_addc_u32 s25, s25, 0
	s_mov_b32 m0, s38
	v_lshl_add_u64 v[222:223], s[24:25], 0, v[128:129]
	ds_read_b128 v[178:181], v141 offset:32768
	ds_read_b128 v[186:189], v141 offset:33792
	ds_read_b128 v[190:193], v141 offset:34816
	ds_read_b128 v[194:197], v141 offset:35840
	ds_read_b128 v[198:201], v141 offset:36864
	ds_read_b128 v[202:205], v141 offset:37888
	ds_read_b128 v[206:209], v141 offset:38912
	ds_read_b128 v[210:213], v141 offset:39936
	global_load_lds_dwordx4 v[222:223], off
	v_lshl_add_u64 v[222:223], s[24:25], 0, v[130:131]
	s_mov_b32 m0, s39
	s_nop 0
	global_load_lds_dwordx4 v[222:223], off
	s_waitcnt vmcnt(8)
	s_waitcnt lgkmcnt(0)
	s_barrier
	s_waitcnt lgkmcnt(0)
	v_mfma_f32_16x16x32_bf16 v[124:127], v[142:145], v[178:181], v[124:127]
	v_mfma_f32_16x16x32_bf16 v[120:123], v[150:153], v[178:181], v[120:123]
	v_mfma_f32_16x16x32_bf16 v[116:119], v[142:145], v[190:193], v[116:119]
	v_mfma_f32_16x16x32_bf16 v[112:115], v[150:153], v[190:193], v[112:115]
	v_mfma_f32_16x16x32_bf16 v[100:103], v[142:145], v[198:201], v[100:103]
	v_mfma_f32_16x16x32_bf16 v[96:99], v[150:153], v[198:201], v[96:99]
	v_mfma_f32_16x16x32_bf16 v[84:87], v[142:145], v[206:209], v[84:87]
	v_mfma_f32_16x16x32_bf16 v[80:83], v[150:153], v[206:209], v[80:83]
	v_mfma_f32_16x16x32_bf16 v[124:127], v[146:149], v[186:189], v[124:127]
	v_mfma_f32_16x16x32_bf16 v[120:123], v[154:157], v[186:189], v[120:123]
	v_mfma_f32_16x16x32_bf16 v[116:119], v[146:149], v[194:197], v[116:119]
	v_mfma_f32_16x16x32_bf16 v[112:115], v[154:157], v[194:197], v[112:115]
	v_mfma_f32_16x16x32_bf16 v[100:103], v[146:149], v[202:205], v[100:103]
	v_mfma_f32_16x16x32_bf16 v[96:99], v[154:157], v[202:205], v[96:99]
	v_mfma_f32_16x16x32_bf16 v[84:87], v[146:149], v[210:213], v[84:87]
	v_mfma_f32_16x16x32_bf16 v[80:83], v[154:157], v[210:213], v[80:83]
	v_mfma_f32_16x16x32_bf16 v[108:111], v[158:161], v[178:181], v[108:111]
	v_mfma_f32_16x16x32_bf16 v[104:107], v[166:169], v[178:181], v[104:107]
	v_mfma_f32_16x16x32_bf16 v[92:95], v[158:161], v[190:193], v[92:95]
	v_mfma_f32_16x16x32_bf16 v[88:91], v[166:169], v[190:193], v[88:91]
	v_mfma_f32_16x16x32_bf16 v[76:79], v[158:161], v[198:201], v[76:79]
	v_mfma_f32_16x16x32_bf16 v[72:75], v[166:169], v[198:201], v[72:75]
	v_mfma_f32_16x16x32_bf16 v[68:71], v[158:161], v[206:209], v[68:71]
	v_mfma_f32_16x16x32_bf16 v[64:67], v[166:169], v[206:209], v[64:67]
	v_mfma_f32_16x16x32_bf16 v[108:111], v[162:165], v[186:189], v[108:111]
	v_mfma_f32_16x16x32_bf16 v[104:107], v[170:173], v[186:189], v[104:107]
	v_mfma_f32_16x16x32_bf16 v[92:95], v[162:165], v[194:197], v[92:95]
	v_mfma_f32_16x16x32_bf16 v[88:91], v[170:173], v[194:197], v[88:91]
	v_mfma_f32_16x16x32_bf16 v[76:79], v[162:165], v[202:205], v[76:79]
	v_mfma_f32_16x16x32_bf16 v[72:75], v[170:173], v[202:205], v[72:75]
	v_mfma_f32_16x16x32_bf16 v[68:71], v[162:165], v[210:213], v[68:71]
	v_mfma_f32_16x16x32_bf16 v[64:67], v[170:173], v[210:213], v[64:67]
	s_barrier
	s_add_i32 s24, s50, s35
	v_lshl_add_u64 v[174:175], v[174:175], 0, s[72:73]
	s_mov_b32 m0, s24
	ds_read_b128 v[178:181], v141 offset:49152
	ds_read_b128 v[186:189], v141 offset:50176
	ds_read_b128 v[190:193], v141 offset:51200
	ds_read_b128 v[194:197], v141 offset:52224
	ds_read_b128 v[198:201], v141 offset:53248
	ds_read_b128 v[202:205], v141 offset:54272
	ds_read_b128 v[206:209], v141 offset:55296
	ds_read_b128 v[210:213], v141 offset:56320
	global_load_lds_dwordx4 v[174:175], off
	s_add_i32 m0, s24, 0x2000
	s_add_u32 s22, s22, 0x40080
	v_lshl_add_u64 v[174:175], v[214:215], 0, s[72:73]
	s_addc_u32 s23, s23, 0
	s_add_i32 s24, s52, s35
	global_load_lds_dwordx4 v[174:175], off
	v_lshl_add_u64 v[174:175], s[22:23], 0, v[176:177]
	s_mov_b32 m0, s24
	s_nop 0
	global_load_lds_dwordx4 v[174:175], off
	v_lshl_add_u64 v[174:175], s[22:23], 0, v[132:133]
	s_add_i32 m0, s24, 0x2000
	s_nop 0
	global_load_lds_dwordx4 v[174:175], off
	v_lshl_add_u64 v[174:175], v[216:217], 0, s[72:73]
	s_mov_b32 m0, s40
	s_nop 0
	global_load_lds_dwordx4 v[174:175], off
	v_lshl_add_u64 v[174:175], v[218:219], 0, s[72:73]
	s_mov_b32 m0, s41
	s_nop 0
	global_load_lds_dwordx4 v[174:175], off
	s_waitcnt vmcnt(8)
	s_waitcnt lgkmcnt(0)
	s_barrier
	s_waitcnt lgkmcnt(0)
	v_mfma_f32_16x16x32_bf16 v[60:63], v[142:145], v[178:181], v[60:63]
	v_mfma_f32_16x16x32_bf16 v[56:59], v[150:153], v[178:181], v[56:59]
	v_mfma_f32_16x16x32_bf16 v[52:55], v[142:145], v[190:193], v[52:55]
	v_mfma_f32_16x16x32_bf16 v[48:51], v[150:153], v[190:193], v[48:51]
	v_mfma_f32_16x16x32_bf16 v[36:39], v[142:145], v[198:201], v[36:39]
	v_mfma_f32_16x16x32_bf16 v[32:35], v[150:153], v[198:201], v[32:35]
	v_mfma_f32_16x16x32_bf16 v[20:23], v[142:145], v[206:209], v[20:23]
	v_mfma_f32_16x16x32_bf16 v[16:19], v[150:153], v[206:209], v[16:19]
	v_mfma_f32_16x16x32_bf16 v[60:63], v[146:149], v[186:189], v[60:63]
	v_mfma_f32_16x16x32_bf16 v[56:59], v[154:157], v[186:189], v[56:59]
	v_mfma_f32_16x16x32_bf16 v[52:55], v[146:149], v[194:197], v[52:55]
	v_mfma_f32_16x16x32_bf16 v[48:51], v[154:157], v[194:197], v[48:51]
	v_mfma_f32_16x16x32_bf16 v[36:39], v[146:149], v[202:205], v[36:39]
	v_mfma_f32_16x16x32_bf16 v[32:35], v[154:157], v[202:205], v[32:35]
	v_mfma_f32_16x16x32_bf16 v[20:23], v[146:149], v[210:213], v[20:23]
	v_mfma_f32_16x16x32_bf16 v[16:19], v[154:157], v[210:213], v[16:19]
	v_mfma_f32_16x16x32_bf16 v[44:47], v[158:161], v[178:181], v[44:47]
	v_mfma_f32_16x16x32_bf16 v[40:43], v[166:169], v[178:181], v[40:43]
	v_mfma_f32_16x16x32_bf16 v[28:31], v[158:161], v[190:193], v[28:31]
	v_mfma_f32_16x16x32_bf16 v[24:27], v[166:169], v[190:193], v[24:27]
	v_mfma_f32_16x16x32_bf16 v[12:15], v[158:161], v[198:201], v[12:15]
	v_mfma_f32_16x16x32_bf16 v[8:11], v[166:169], v[198:201], v[8:11]
	v_mfma_f32_16x16x32_bf16 v[4:7], v[158:161], v[206:209], v[4:7]
	v_mfma_f32_16x16x32_bf16 v[0:3], v[166:169], v[206:209], v[0:3]
	v_mfma_f32_16x16x32_bf16 v[44:47], v[162:165], v[186:189], v[44:47]
	v_mfma_f32_16x16x32_bf16 v[40:43], v[170:173], v[186:189], v[40:43]
	v_mfma_f32_16x16x32_bf16 v[28:31], v[162:165], v[194:197], v[28:31]
	v_mfma_f32_16x16x32_bf16 v[24:27], v[170:173], v[194:197], v[24:27]
	v_mfma_f32_16x16x32_bf16 v[12:15], v[162:165], v[202:205], v[12:15]
	v_mfma_f32_16x16x32_bf16 v[8:11], v[170:173], v[202:205], v[8:11]
	v_mfma_f32_16x16x32_bf16 v[4:7], v[162:165], v[210:213], v[4:7]
	v_mfma_f32_16x16x32_bf16 v[0:3], v[170:173], v[210:213], v[0:3]
	s_barrier
	s_add_i32 s49, s49, 2
	s_add_u32 s46, s46, 0x100
	s_addc_u32 s48, s48, 0
	s_add_u32 s20, s20, 0x100
	s_addc_u32 s21, s21, 0
	s_cmp_gt_u32 s49, 13
	s_cbranch_scc0 .LBB0_732
	s_and_b64 vcc, exec, s[6:7]
	s_cbranch_vccz .LBB0_735
	s_barrier

.LBB0_1322:
	s_add_u32 s30, s28, 0xfffc0080
	s_addc_u32 s31, s29, -1
	s_add_i32 s63, 0, 0x10000
	s_cmp_eq_u32 s50, 12
	s_cselect_b32 s37, s7, s31
	s_cselect_b32 s36, s21, s30
	s_cselect_b32 s31, s19, s43
	s_cselect_b32 s30, s27, s42
	s_add_i32 s66, 0, 0x14000
	v_add_u32_e32 v68, s63, v173
	v_add_u32_e32 v166, s66, v173
	ds_read_b128 v[48:51], v68
	ds_read_b128 v[52:55], v68 offset:1024
	ds_read_b128 v[64:67], v68 offset:2048
	ds_read_b128 v[68:71], v68 offset:3072
	ds_read_b128 v[144:147], v166
	ds_read_b128 v[148:151], v166 offset:1024
	ds_read_b128 v[162:165], v166 offset:2048
	ds_read_b128 v[166:169], v166 offset:3072
	v_lshl_add_u64 v[170:171], s[28:29], 0, v[160:161]
	s_add_i32 m0, s52, 0xc000
	ds_read_b128 v[178:181], v175
	ds_read_b128 v[186:189], v175 offset:1024
	ds_read_b128 v[190:193], v175 offset:2048
	ds_read_b128 v[194:197], v175 offset:3072
	ds_read_b128 v[198:201], v175 offset:4096
	ds_read_b128 v[202:205], v175 offset:5120
	ds_read_b128 v[206:209], v175 offset:6144
	ds_read_b128 v[210:213], v175 offset:7168
	global_load_lds_dwordx4 v[170:171], off
	v_lshl_add_u64 v[170:171], s[28:29], 0, v[158:159]
	s_add_i32 m0, s52, 0xe000
	s_nop 0
	global_load_lds_dwordx4 v[170:171], off
	s_waitcnt vmcnt(8)
	s_waitcnt lgkmcnt(0)
	s_barrier
	s_waitcnt lgkmcnt(0)
	v_mfma_f32_16x16x32_bf16 v[140:143], v[48:51], v[178:181], v[140:143]
	v_mfma_f32_16x16x32_bf16 v[136:139], v[64:67], v[178:181], v[136:139]
	v_mfma_f32_16x16x32_bf16 v[124:127], v[48:51], v[190:193], v[124:127]
	v_mfma_f32_16x16x32_bf16 v[120:123], v[64:67], v[190:193], v[120:123]
	v_mfma_f32_16x16x32_bf16 v[108:111], v[48:51], v[198:201], v[108:111]
	v_mfma_f32_16x16x32_bf16 v[104:107], v[64:67], v[198:201], v[104:107]
	v_mfma_f32_16x16x32_bf16 v[92:95], v[48:51], v[206:209], v[92:95]
	v_mfma_f32_16x16x32_bf16 v[88:91], v[64:67], v[206:209], v[88:91]
	v_mfma_f32_16x16x32_bf16 v[140:143], v[52:55], v[186:189], v[140:143]
	v_mfma_f32_16x16x32_bf16 v[136:139], v[68:71], v[186:189], v[136:139]
	v_mfma_f32_16x16x32_bf16 v[124:127], v[52:55], v[194:197], v[124:127]
	v_mfma_f32_16x16x32_bf16 v[120:123], v[68:71], v[194:197], v[120:123]
	v_mfma_f32_16x16x32_bf16 v[108:111], v[52:55], v[202:205], v[108:111]
	v_mfma_f32_16x16x32_bf16 v[104:107], v[68:71], v[202:205], v[104:107]
	v_mfma_f32_16x16x32_bf16 v[92:95], v[52:55], v[210:213], v[92:95]
	v_mfma_f32_16x16x32_bf16 v[88:91], v[68:71], v[210:213], v[88:91]
	v_mfma_f32_16x16x32_bf16 v[132:135], v[144:147], v[178:181], v[132:135]
	v_mfma_f32_16x16x32_bf16 v[128:131], v[162:165], v[178:181], v[128:131]
	v_mfma_f32_16x16x32_bf16 v[116:119], v[144:147], v[190:193], v[116:119]
	v_mfma_f32_16x16x32_bf16 v[112:115], v[162:165], v[190:193], v[112:115]
	v_mfma_f32_16x16x32_bf16 v[100:103], v[144:147], v[198:201], v[100:103]
	v_mfma_f32_16x16x32_bf16 v[96:99], v[162:165], v[198:201], v[96:99]
	v_mfma_f32_16x16x32_bf16 v[84:87], v[144:147], v[206:209], v[84:87]
	v_mfma_f32_16x16x32_bf16 v[80:83], v[162:165], v[206:209], v[80:83]
	v_mfma_f32_16x16x32_bf16 v[132:135], v[148:151], v[186:189], v[132:135]
	v_mfma_f32_16x16x32_bf16 v[128:131], v[166:169], v[186:189], v[128:131]
	v_mfma_f32_16x16x32_bf16 v[116:119], v[148:151], v[194:197], v[116:119]
	v_mfma_f32_16x16x32_bf16 v[112:115], v[166:169], v[194:197], v[112:115]
	v_mfma_f32_16x16x32_bf16 v[100:103], v[148:151], v[202:205], v[100:103]
	v_mfma_f32_16x16x32_bf16 v[96:99], v[166:169], v[202:205], v[96:99]
	v_mfma_f32_16x16x32_bf16 v[84:87], v[148:151], v[210:213], v[84:87]
	v_mfma_f32_16x16x32_bf16 v[80:83], v[166:169], v[210:213], v[80:83]
	s_barrier
	s_add_i32 s63, s63, s49
	v_lshl_add_u64 v[170:171], s[30:31], 0, v[176:177]
	s_mov_b32 m0, s63
	ds_read_b128 v[178:181], v175 offset:16384
	ds_read_b128 v[186:189], v175 offset:17408
	ds_read_b128 v[190:193], v175 offset:18432
	ds_read_b128 v[194:197], v175 offset:19456
	ds_read_b128 v[198:201], v175 offset:20480
	ds_read_b128 v[202:205], v175 offset:21504
	ds_read_b128 v[206:209], v175 offset:22528
	ds_read_b128 v[210:213], v175 offset:23552
	global_load_lds_dwordx4 v[170:171], off
	s_add_i32 m0, s63, 0x2000
	s_add_u32 s64, s30, 0x40000
	v_lshl_add_u64 v[182:183], s[30:31], 0, v[156:157]
	s_addc_u32 s65, s31, 0
	s_add_i32 s63, s66, s49
	global_load_lds_dwordx4 v[182:183], off
	v_lshl_add_u64 v[184:185], s[64:65], 0, v[176:177]
	s_mov_b32 m0, s63
	v_lshl_add_u64 v[214:215], s[36:37], 0, v[154:155]
	global_load_lds_dwordx4 v[184:185], off
	v_lshl_add_u64 v[184:185], s[64:65], 0, v[156:157]
	s_add_i32 m0, s63, 0x2000
	s_nop 0
	global_load_lds_dwordx4 v[184:185], off
	v_lshl_add_u64 v[184:185], s[36:37], 0, v[152:153]
	s_mov_b32 m0, s52
	s_nop 0
	global_load_lds_dwordx4 v[184:185], off
	s_mov_b32 m0, s53
	s_nop 0
	global_load_lds_dwordx4 v[214:215], off
	s_waitcnt vmcnt(8)
	s_waitcnt lgkmcnt(0)
	s_barrier
	s_waitcnt lgkmcnt(0)
	v_mfma_f32_16x16x32_bf16 v[76:79], v[48:51], v[178:181], v[76:79]
	v_mfma_f32_16x16x32_bf16 v[72:75], v[64:67], v[178:181], v[72:75]
	v_mfma_f32_16x16x32_bf16 v[44:47], v[48:51], v[190:193], v[44:47]
	v_mfma_f32_16x16x32_bf16 v[40:43], v[64:67], v[190:193], v[40:43]
	v_mfma_f32_16x16x32_bf16 v[28:31], v[48:51], v[198:201], v[28:31]
	v_mfma_f32_16x16x32_bf16 v[24:27], v[64:67], v[198:201], v[24:27]
	v_mfma_f32_16x16x32_bf16 v[12:15], v[48:51], v[206:209], v[12:15]
	v_mfma_f32_16x16x32_bf16 v[8:11], v[64:67], v[206:209], v[8:11]
	v_mfma_f32_16x16x32_bf16 v[76:79], v[52:55], v[186:189], v[76:79]
	v_mfma_f32_16x16x32_bf16 v[72:75], v[68:71], v[186:189], v[72:75]
	v_mfma_f32_16x16x32_bf16 v[44:47], v[52:55], v[194:197], v[44:47]
	v_mfma_f32_16x16x32_bf16 v[40:43], v[68:71], v[194:197], v[40:43]
	v_mfma_f32_16x16x32_bf16 v[28:31], v[52:55], v[202:205], v[28:31]
	v_mfma_f32_16x16x32_bf16 v[24:27], v[68:71], v[202:205], v[24:27]
	v_mfma_f32_16x16x32_bf16 v[12:15], v[52:55], v[210:213], v[12:15]
	v_mfma_f32_16x16x32_bf16 v[8:11], v[68:71], v[210:213], v[8:11]
	v_mfma_f32_16x16x32_bf16 v[36:39], v[144:147], v[190:193], v[36:39]
	v_mfma_f32_16x16x32_bf16 v[32:35], v[162:165], v[190:193], v[32:35]
	v_mfma_f32_16x16x32_bf16 v[20:23], v[144:147], v[198:201], v[20:23]
	v_mfma_f32_16x16x32_bf16 v[16:19], v[162:165], v[198:201], v[16:19]
	v_mfma_f32_16x16x32_bf16 v[4:7], v[144:147], v[206:209], v[4:7]
	v_mfma_f32_16x16x32_bf16 v[0:3], v[162:165], v[206:209], v[0:3]
	v_mfma_f32_16x16x32_bf16 v[48:51], v[144:147], v[178:181], v[60:63]
	v_mfma_f32_16x16x32_bf16 v[52:55], v[162:165], v[178:181], v[56:59]
	v_mfma_f32_16x16x32_bf16 v[36:39], v[148:151], v[194:197], v[36:39]
	v_mfma_f32_16x16x32_bf16 v[32:35], v[166:169], v[194:197], v[32:35]
	v_mfma_f32_16x16x32_bf16 v[20:23], v[148:151], v[202:205], v[20:23]
	v_mfma_f32_16x16x32_bf16 v[16:19], v[166:169], v[202:205], v[16:19]
	v_mfma_f32_16x16x32_bf16 v[4:7], v[148:151], v[210:213], v[4:7]
	v_mfma_f32_16x16x32_bf16 v[0:3], v[166:169], v[210:213], v[0:3]
	v_mfma_f32_16x16x32_bf16 v[48:51], v[148:151], v[186:189], v[48:51]
	v_mfma_f32_16x16x32_bf16 v[52:55], v[166:169], v[186:189], v[52:55]
	s_barrier
	s_add_i32 s63, 0, 0x18000
	s_add_i32 s64, 0, 0x1c000
	v_add_u32_e32 v68, s63, v173
	v_add_u32_e32 v166, s64, v173
	ds_read_b128 v[56:59], v68
	ds_read_b128 v[60:63], v68 offset:1024
	ds_read_b128 v[64:67], v68 offset:2048
	ds_read_b128 v[68:71], v68 offset:3072
	ds_read_b128 v[144:147], v166
	ds_read_b128 v[148:151], v166 offset:1024
	ds_read_b128 v[162:165], v166 offset:2048
	ds_read_b128 v[166:169], v166 offset:3072
	s_add_u32 s36, s36, 0x40000
	s_addc_u32 s37, s37, 0
	s_mov_b32 m0, s56
	v_lshl_add_u64 v[216:217], s[36:37], 0, v[152:153]
	ds_read_b128 v[178:181], v175 offset:32768
	ds_read_b128 v[186:189], v175 offset:33792
	ds_read_b128 v[190:193], v175 offset:34816
	ds_read_b128 v[194:197], v175 offset:35840
	ds_read_b128 v[198:201], v175 offset:36864
	ds_read_b128 v[202:205], v175 offset:37888
	ds_read_b128 v[206:209], v175 offset:38912
	ds_read_b128 v[210:213], v175 offset:39936
	global_load_lds_dwordx4 v[216:217], off
	v_lshl_add_u64 v[216:217], s[36:37], 0, v[154:155]
	s_mov_b32 m0, s57
	s_nop 0
	global_load_lds_dwordx4 v[216:217], off
	s_waitcnt vmcnt(8)
	s_waitcnt lgkmcnt(0)
	s_barrier
	s_waitcnt lgkmcnt(0)
	v_mfma_f32_16x16x32_bf16 v[140:143], v[56:59], v[178:181], v[140:143]
	v_mfma_f32_16x16x32_bf16 v[136:139], v[64:67], v[178:181], v[136:139]
	v_mfma_f32_16x16x32_bf16 v[124:127], v[56:59], v[190:193], v[124:127]
	v_mfma_f32_16x16x32_bf16 v[120:123], v[64:67], v[190:193], v[120:123]
	v_mfma_f32_16x16x32_bf16 v[108:111], v[56:59], v[198:201], v[108:111]
	v_mfma_f32_16x16x32_bf16 v[104:107], v[64:67], v[198:201], v[104:107]
	v_mfma_f32_16x16x32_bf16 v[92:95], v[56:59], v[206:209], v[92:95]
	v_mfma_f32_16x16x32_bf16 v[88:91], v[64:67], v[206:209], v[88:91]
	v_mfma_f32_16x16x32_bf16 v[140:143], v[60:63], v[186:189], v[140:143]
	v_mfma_f32_16x16x32_bf16 v[136:139], v[68:71], v[186:189], v[136:139]
	v_mfma_f32_16x16x32_bf16 v[124:127], v[60:63], v[194:197], v[124:127]
	v_mfma_f32_16x16x32_bf16 v[120:123], v[68:71], v[194:197], v[120:123]
	v_mfma_f32_16x16x32_bf16 v[108:111], v[60:63], v[202:205], v[108:111]
	v_mfma_f32_16x16x32_bf16 v[104:107], v[68:71], v[202:205], v[104:107]
	v_mfma_f32_16x16x32_bf16 v[92:95], v[60:63], v[210:213], v[92:95]
	v_mfma_f32_16x16x32_bf16 v[88:91], v[68:71], v[210:213], v[88:91]
	v_mfma_f32_16x16x32_bf16 v[132:135], v[144:147], v[178:181], v[132:135]
	v_mfma_f32_16x16x32_bf16 v[128:131], v[162:165], v[178:181], v[128:131]
	v_mfma_f32_16x16x32_bf16 v[116:119], v[144:147], v[190:193], v[116:119]
	v_mfma_f32_16x16x32_bf16 v[112:115], v[162:165], v[190:193], v[112:115]
	v_mfma_f32_16x16x32_bf16 v[100:103], v[144:147], v[198:201], v[100:103]
	v_mfma_f32_16x16x32_bf16 v[96:99], v[162:165], v[198:201], v[96:99]
	v_mfma_f32_16x16x32_bf16 v[84:87], v[144:147], v[206:209], v[84:87]
	v_mfma_f32_16x16x32_bf16 v[80:83], v[162:165], v[206:209], v[80:83]
	v_mfma_f32_16x16x32_bf16 v[132:135], v[148:151], v[186:189], v[132:135]
	v_mfma_f32_16x16x32_bf16 v[128:131], v[166:169], v[186:189], v[128:131]
	v_mfma_f32_16x16x32_bf16 v[116:119], v[148:151], v[194:197], v[116:119]
	v_mfma_f32_16x16x32_bf16 v[112:115], v[166:169], v[194:197], v[112:115]
	v_mfma_f32_16x16x32_bf16 v[100:103], v[148:151], v[202:205], v[100:103]
	v_mfma_f32_16x16x32_bf16 v[96:99], v[166:169], v[202:205], v[96:99]
	v_mfma_f32_16x16x32_bf16 v[84:87], v[148:151], v[210:213], v[84:87]
	v_mfma_f32_16x16x32_bf16 v[80:83], v[166:169], v[210:213], v[80:83]
	s_barrier
	s_add_i32 s36, s63, s49
	v_lshl_add_u64 v[170:171], v[170:171], 0, s[72:73]
	s_mov_b32 m0, s36
	ds_read_b128 v[178:181], v175 offset:49152
	ds_read_b128 v[186:189], v175 offset:50176
	ds_read_b128 v[190:193], v175 offset:51200
	ds_read_b128 v[194:197], v175 offset:52224
	ds_read_b128 v[198:201], v175 offset:53248
	ds_read_b128 v[202:205], v175 offset:54272
	ds_read_b128 v[206:209], v175 offset:55296
	ds_read_b128 v[210:213], v175 offset:56320
	global_load_lds_dwordx4 v[170:171], off
	s_add_i32 m0, s36, 0x2000
	s_add_u32 s30, s30, 0x40080
	v_lshl_add_u64 v[170:171], v[182:183], 0, s[72:73]
	s_addc_u32 s31, s31, 0
	s_add_i32 s36, s64, s49
	global_load_lds_dwordx4 v[170:171], off
	v_lshl_add_u64 v[170:171], s[30:31], 0, v[176:177]
	s_mov_b32 m0, s36
	s_nop 0
	global_load_lds_dwordx4 v[170:171], off
	v_lshl_add_u64 v[170:171], s[30:31], 0, v[156:157]
	s_add_i32 m0, s36, 0x2000
	s_nop 0
	global_load_lds_dwordx4 v[170:171], off
	v_lshl_add_u64 v[170:171], v[184:185], 0, s[72:73]
	s_mov_b32 m0, s58
	s_nop 0
	global_load_lds_dwordx4 v[170:171], off
	v_lshl_add_u64 v[170:171], v[214:215], 0, s[72:73]
	s_mov_b32 m0, s59
	s_nop 0
	global_load_lds_dwordx4 v[170:171], off
	s_waitcnt vmcnt(8)
	s_waitcnt lgkmcnt(0)
	s_barrier
	s_waitcnt lgkmcnt(0)
	v_mfma_f32_16x16x32_bf16 v[76:79], v[56:59], v[178:181], v[76:79]
	v_mfma_f32_16x16x32_bf16 v[72:75], v[64:67], v[178:181], v[72:75]
	v_mfma_f32_16x16x32_bf16 v[44:47], v[56:59], v[190:193], v[44:47]
	v_mfma_f32_16x16x32_bf16 v[40:43], v[64:67], v[190:193], v[40:43]
	v_mfma_f32_16x16x32_bf16 v[28:31], v[56:59], v[198:201], v[28:31]
	v_mfma_f32_16x16x32_bf16 v[24:27], v[64:67], v[198:201], v[24:27]
	v_mfma_f32_16x16x32_bf16 v[12:15], v[56:59], v[206:209], v[12:15]
	v_mfma_f32_16x16x32_bf16 v[8:11], v[64:67], v[206:209], v[8:11]
	v_mfma_f32_16x16x32_bf16 v[76:79], v[60:63], v[186:189], v[76:79]
	v_mfma_f32_16x16x32_bf16 v[72:75], v[68:71], v[186:189], v[72:75]
	v_mfma_f32_16x16x32_bf16 v[44:47], v[60:63], v[194:197], v[44:47]
	v_mfma_f32_16x16x32_bf16 v[40:43], v[68:71], v[194:197], v[40:43]
	v_mfma_f32_16x16x32_bf16 v[28:31], v[60:63], v[202:205], v[28:31]
	v_mfma_f32_16x16x32_bf16 v[24:27], v[68:71], v[202:205], v[24:27]
	v_mfma_f32_16x16x32_bf16 v[12:15], v[60:63], v[210:213], v[12:15]
	v_mfma_f32_16x16x32_bf16 v[8:11], v[68:71], v[210:213], v[8:11]
	v_mfma_f32_16x16x32_bf16 v[48:51], v[144:147], v[178:181], v[48:51]
	v_mfma_f32_16x16x32_bf16 v[60:63], v[148:151], v[186:189], v[48:51]
	v_mfma_f32_16x16x32_bf16 v[48:51], v[162:165], v[178:181], v[52:55]
	v_mfma_f32_16x16x32_bf16 v[36:39], v[144:147], v[190:193], v[36:39]
	v_mfma_f32_16x16x32_bf16 v[32:35], v[162:165], v[190:193], v[32:35]
	v_mfma_f32_16x16x32_bf16 v[20:23], v[144:147], v[198:201], v[20:23]
	v_mfma_f32_16x16x32_bf16 v[16:19], v[162:165], v[198:201], v[16:19]
	v_mfma_f32_16x16x32_bf16 v[4:7], v[144:147], v[206:209], v[4:7]
	v_mfma_f32_16x16x32_bf16 v[0:3], v[162:165], v[206:209], v[0:3]
	v_mfma_f32_16x16x32_bf16 v[56:59], v[166:169], v[186:189], v[48:51]
	v_mfma_f32_16x16x32_bf16 v[36:39], v[148:151], v[194:197], v[36:39]
	v_mfma_f32_16x16x32_bf16 v[32:35], v[166:169], v[194:197], v[32:35]
	v_mfma_f32_16x16x32_bf16 v[20:23], v[148:151], v[202:205], v[20:23]
	v_mfma_f32_16x16x32_bf16 v[16:19], v[166:169], v[202:205], v[16:19]
	v_mfma_f32_16x16x32_bf16 v[4:7], v[148:151], v[210:213], v[4:7]
	v_mfma_f32_16x16x32_bf16 v[0:3], v[166:169], v[210:213], v[0:3]
	s_barrier
	s_add_i32 s50, s50, 2
	s_add_u32 s42, s42, 0x100
	s_addc_u32 s43, s43, 0
	s_add_u32 s28, s28, 0x100
	s_addc_u32 s29, s29, 0
	s_cmp_gt_u32 s50, 13
	s_cbranch_scc0 .LBB0_1322
	s_and_b64 vcc, exec, s[16:17]
	s_cbranch_vccz .LBB0_1325
	s_barrier

.LBB0_1472:
	s_add_u32 s24, s22, 0xfffc0080
	s_addc_u32 s25, s23, -1
	s_add_i32 s61, 0, 0x10000
	s_cmp_eq_u32 s60, 12
	s_cselect_b32 s27, s15, s25
	s_cselect_b32 s26, s42, s24
	s_cselect_b32 s25, s13, s59
	s_cselect_b32 s24, s43, s50
	s_add_i32 s64, 0, 0x14000
	v_add_u32_e32 v154, s61, v143
	v_add_u32_e32 v170, s64, v143
	ds_read_b128 v[138:141], v154
	ds_read_b128 v[146:149], v154 offset:1024
	ds_read_b128 v[150:153], v154 offset:2048
	ds_read_b128 v[154:157], v154 offset:3072
	ds_read_b128 v[158:161], v170
	ds_read_b128 v[162:165], v170 offset:1024
	ds_read_b128 v[166:169], v170 offset:2048
	ds_read_b128 v[170:173], v170 offset:3072
	v_lshl_add_u64 v[174:175], s[22:23], 0, v[136:137]
	s_add_i32 m0, s46, 0xc000
	ds_read_b128 v[178:181], v145
	ds_read_b128 v[186:189], v145 offset:1024
	ds_read_b128 v[190:193], v145 offset:2048
	ds_read_b128 v[194:197], v145 offset:3072
	ds_read_b128 v[198:201], v145 offset:4096
	ds_read_b128 v[202:205], v145 offset:5120
	ds_read_b128 v[206:209], v145 offset:6144
	ds_read_b128 v[210:213], v145 offset:7168
	global_load_lds_dwordx4 v[174:175], off
	v_lshl_add_u64 v[174:175], s[22:23], 0, v[134:135]
	s_add_i32 m0, s46, 0xe000
	s_nop 0
	global_load_lds_dwordx4 v[174:175], off
	s_waitcnt vmcnt(8)
	s_waitcnt lgkmcnt(0)
	s_barrier
	s_waitcnt lgkmcnt(0)
	v_mfma_f32_16x16x32_bf16 v[124:127], v[138:141], v[178:181], v[124:127]
	v_mfma_f32_16x16x32_bf16 v[120:123], v[150:153], v[178:181], v[120:123]
	v_mfma_f32_16x16x32_bf16 v[108:111], v[138:141], v[190:193], v[108:111]
	v_mfma_f32_16x16x32_bf16 v[104:107], v[150:153], v[190:193], v[104:107]
	v_mfma_f32_16x16x32_bf16 v[92:95], v[138:141], v[198:201], v[92:95]
	v_mfma_f32_16x16x32_bf16 v[88:91], v[150:153], v[198:201], v[88:91]
	v_mfma_f32_16x16x32_bf16 v[76:79], v[138:141], v[206:209], v[76:79]
	v_mfma_f32_16x16x32_bf16 v[72:75], v[150:153], v[206:209], v[72:75]
	v_mfma_f32_16x16x32_bf16 v[124:127], v[146:149], v[186:189], v[124:127]
	v_mfma_f32_16x16x32_bf16 v[120:123], v[154:157], v[186:189], v[120:123]
	v_mfma_f32_16x16x32_bf16 v[108:111], v[146:149], v[194:197], v[108:111]
	v_mfma_f32_16x16x32_bf16 v[104:107], v[154:157], v[194:197], v[104:107]
	v_mfma_f32_16x16x32_bf16 v[92:95], v[146:149], v[202:205], v[92:95]
	v_mfma_f32_16x16x32_bf16 v[88:91], v[154:157], v[202:205], v[88:91]
	v_mfma_f32_16x16x32_bf16 v[76:79], v[146:149], v[210:213], v[76:79]
	v_mfma_f32_16x16x32_bf16 v[72:75], v[154:157], v[210:213], v[72:75]
	v_mfma_f32_16x16x32_bf16 v[116:119], v[158:161], v[178:181], v[116:119]
	v_mfma_f32_16x16x32_bf16 v[112:115], v[166:169], v[178:181], v[112:115]
	v_mfma_f32_16x16x32_bf16 v[100:103], v[158:161], v[190:193], v[100:103]
	v_mfma_f32_16x16x32_bf16 v[96:99], v[166:169], v[190:193], v[96:99]
	v_mfma_f32_16x16x32_bf16 v[84:87], v[158:161], v[198:201], v[84:87]
	v_mfma_f32_16x16x32_bf16 v[80:83], v[166:169], v[198:201], v[80:83]
	v_mfma_f32_16x16x32_bf16 v[68:71], v[158:161], v[206:209], v[68:71]
	v_mfma_f32_16x16x32_bf16 v[64:67], v[166:169], v[206:209], v[64:67]
	v_mfma_f32_16x16x32_bf16 v[116:119], v[162:165], v[186:189], v[116:119]
	v_mfma_f32_16x16x32_bf16 v[112:115], v[170:173], v[186:189], v[112:115]
	v_mfma_f32_16x16x32_bf16 v[100:103], v[162:165], v[194:197], v[100:103]
	v_mfma_f32_16x16x32_bf16 v[96:99], v[170:173], v[194:197], v[96:99]
	v_mfma_f32_16x16x32_bf16 v[84:87], v[162:165], v[202:205], v[84:87]
	v_mfma_f32_16x16x32_bf16 v[80:83], v[170:173], v[202:205], v[80:83]
	v_mfma_f32_16x16x32_bf16 v[68:71], v[162:165], v[210:213], v[68:71]
	v_mfma_f32_16x16x32_bf16 v[64:67], v[170:173], v[210:213], v[64:67]
	s_barrier
	s_add_i32 s61, s61, s45
	v_lshl_add_u64 v[174:175], s[24:25], 0, v[176:177]
	s_mov_b32 m0, s61
	ds_read_b128 v[178:181], v145 offset:16384
	ds_read_b128 v[186:189], v145 offset:17408
	ds_read_b128 v[190:193], v145 offset:18432
	ds_read_b128 v[194:197], v145 offset:19456
	ds_read_b128 v[198:201], v145 offset:20480
	ds_read_b128 v[202:205], v145 offset:21504
	ds_read_b128 v[206:209], v145 offset:22528
	ds_read_b128 v[210:213], v145 offset:23552
	global_load_lds_dwordx4 v[174:175], off
	s_add_i32 m0, s61, 0x2000
	s_add_u32 s62, s24, 0x40000
	v_lshl_add_u64 v[182:183], s[24:25], 0, v[132:133]
	s_addc_u32 s63, s25, 0
	s_add_i32 s61, s64, s45
	global_load_lds_dwordx4 v[182:183], off
	v_lshl_add_u64 v[184:185], s[62:63], 0, v[176:177]
	s_mov_b32 m0, s61
	v_lshl_add_u64 v[214:215], s[26:27], 0, v[130:131]
	global_load_lds_dwordx4 v[184:185], off
	v_lshl_add_u64 v[184:185], s[62:63], 0, v[132:133]
	s_add_i32 m0, s61, 0x2000
	s_nop 0
	global_load_lds_dwordx4 v[184:185], off
	v_lshl_add_u64 v[184:185], s[26:27], 0, v[128:129]
	s_mov_b32 m0, s46
	s_nop 0
	global_load_lds_dwordx4 v[184:185], off
	s_mov_b32 m0, s48
	s_nop 0
	global_load_lds_dwordx4 v[214:215], off
	s_waitcnt vmcnt(8)
	s_waitcnt lgkmcnt(0)
	s_barrier
	s_waitcnt lgkmcnt(0)
	v_mfma_f32_16x16x32_bf16 v[60:63], v[138:141], v[178:181], v[60:63]
	v_mfma_f32_16x16x32_bf16 v[56:59], v[150:153], v[178:181], v[56:59]
	v_mfma_f32_16x16x32_bf16 v[44:47], v[138:141], v[190:193], v[44:47]
	v_mfma_f32_16x16x32_bf16 v[40:43], v[150:153], v[190:193], v[40:43]
	v_mfma_f32_16x16x32_bf16 v[28:31], v[138:141], v[198:201], v[28:31]
	v_mfma_f32_16x16x32_bf16 v[24:27], v[150:153], v[198:201], v[24:27]
	v_mfma_f32_16x16x32_bf16 v[12:15], v[138:141], v[206:209], v[12:15]
	v_mfma_f32_16x16x32_bf16 v[8:11], v[150:153], v[206:209], v[8:11]
	v_mfma_f32_16x16x32_bf16 v[60:63], v[146:149], v[186:189], v[60:63]
	v_mfma_f32_16x16x32_bf16 v[56:59], v[154:157], v[186:189], v[56:59]
	v_mfma_f32_16x16x32_bf16 v[44:47], v[146:149], v[194:197], v[44:47]
	v_mfma_f32_16x16x32_bf16 v[40:43], v[154:157], v[194:197], v[40:43]
	v_mfma_f32_16x16x32_bf16 v[28:31], v[146:149], v[202:205], v[28:31]
	v_mfma_f32_16x16x32_bf16 v[24:27], v[154:157], v[202:205], v[24:27]
	v_mfma_f32_16x16x32_bf16 v[12:15], v[146:149], v[210:213], v[12:15]
	v_mfma_f32_16x16x32_bf16 v[8:11], v[154:157], v[210:213], v[8:11]
	v_mfma_f32_16x16x32_bf16 v[52:55], v[158:161], v[178:181], v[52:55]
	v_mfma_f32_16x16x32_bf16 v[48:51], v[166:169], v[178:181], v[48:51]
	v_mfma_f32_16x16x32_bf16 v[36:39], v[158:161], v[190:193], v[36:39]
	v_mfma_f32_16x16x32_bf16 v[32:35], v[166:169], v[190:193], v[32:35]
	v_mfma_f32_16x16x32_bf16 v[20:23], v[158:161], v[198:201], v[20:23]
	v_mfma_f32_16x16x32_bf16 v[16:19], v[166:169], v[198:201], v[16:19]
	v_mfma_f32_16x16x32_bf16 v[4:7], v[158:161], v[206:209], v[4:7]
	v_mfma_f32_16x16x32_bf16 v[0:3], v[166:169], v[206:209], v[0:3]
	v_mfma_f32_16x16x32_bf16 v[52:55], v[162:165], v[186:189], v[52:55]
	v_mfma_f32_16x16x32_bf16 v[48:51], v[170:173], v[186:189], v[48:51]
	v_mfma_f32_16x16x32_bf16 v[36:39], v[162:165], v[194:197], v[36:39]
	v_mfma_f32_16x16x32_bf16 v[32:35], v[170:173], v[194:197], v[32:35]
	v_mfma_f32_16x16x32_bf16 v[20:23], v[162:165], v[202:205], v[20:23]
	v_mfma_f32_16x16x32_bf16 v[16:19], v[170:173], v[202:205], v[16:19]
	v_mfma_f32_16x16x32_bf16 v[4:7], v[162:165], v[210:213], v[4:7]
	v_mfma_f32_16x16x32_bf16 v[0:3], v[170:173], v[210:213], v[0:3]
	s_barrier
	s_add_i32 s61, 0, 0x18000
	s_add_i32 s62, 0, 0x1c000
	v_add_u32_e32 v154, s61, v143
	v_add_u32_e32 v170, s62, v143
	ds_read_b128 v[138:141], v154
	ds_read_b128 v[146:149], v154 offset:1024
	ds_read_b128 v[150:153], v154 offset:2048
	ds_read_b128 v[154:157], v154 offset:3072
	ds_read_b128 v[158:161], v170
	ds_read_b128 v[162:165], v170 offset:1024
	ds_read_b128 v[166:169], v170 offset:2048
	ds_read_b128 v[170:173], v170 offset:3072
	s_add_u32 s26, s26, 0x40000
	s_addc_u32 s27, s27, 0
	s_mov_b32 m0, s49
	v_lshl_add_u64 v[216:217], s[26:27], 0, v[128:129]
	ds_read_b128 v[178:181], v145 offset:32768
	ds_read_b128 v[186:189], v145 offset:33792
	ds_read_b128 v[190:193], v145 offset:34816
	ds_read_b128 v[194:197], v145 offset:35840
	ds_read_b128 v[198:201], v145 offset:36864
	ds_read_b128 v[202:205], v145 offset:37888
	ds_read_b128 v[206:209], v145 offset:38912
	ds_read_b128 v[210:213], v145 offset:39936
	global_load_lds_dwordx4 v[216:217], off
	v_lshl_add_u64 v[216:217], s[26:27], 0, v[130:131]
	s_mov_b32 m0, s52
	s_nop 0
	global_load_lds_dwordx4 v[216:217], off
	s_waitcnt vmcnt(8)
	s_waitcnt lgkmcnt(0)
	s_barrier
	s_waitcnt lgkmcnt(0)
	v_mfma_f32_16x16x32_bf16 v[124:127], v[138:141], v[178:181], v[124:127]
	v_mfma_f32_16x16x32_bf16 v[120:123], v[150:153], v[178:181], v[120:123]
	v_mfma_f32_16x16x32_bf16 v[108:111], v[138:141], v[190:193], v[108:111]
	v_mfma_f32_16x16x32_bf16 v[104:107], v[150:153], v[190:193], v[104:107]
	v_mfma_f32_16x16x32_bf16 v[92:95], v[138:141], v[198:201], v[92:95]
	v_mfma_f32_16x16x32_bf16 v[88:91], v[150:153], v[198:201], v[88:91]
	v_mfma_f32_16x16x32_bf16 v[76:79], v[138:141], v[206:209], v[76:79]
	v_mfma_f32_16x16x32_bf16 v[72:75], v[150:153], v[206:209], v[72:75]
	v_mfma_f32_16x16x32_bf16 v[124:127], v[146:149], v[186:189], v[124:127]
	v_mfma_f32_16x16x32_bf16 v[120:123], v[154:157], v[186:189], v[120:123]
	v_mfma_f32_16x16x32_bf16 v[108:111], v[146:149], v[194:197], v[108:111]
	v_mfma_f32_16x16x32_bf16 v[104:107], v[154:157], v[194:197], v[104:107]
	v_mfma_f32_16x16x32_bf16 v[92:95], v[146:149], v[202:205], v[92:95]
	v_mfma_f32_16x16x32_bf16 v[88:91], v[154:157], v[202:205], v[88:91]
	v_mfma_f32_16x16x32_bf16 v[76:79], v[146:149], v[210:213], v[76:79]
	v_mfma_f32_16x16x32_bf16 v[72:75], v[154:157], v[210:213], v[72:75]
	v_mfma_f32_16x16x32_bf16 v[116:119], v[158:161], v[178:181], v[116:119]
	v_mfma_f32_16x16x32_bf16 v[112:115], v[166:169], v[178:181], v[112:115]
	v_mfma_f32_16x16x32_bf16 v[100:103], v[158:161], v[190:193], v[100:103]
	v_mfma_f32_16x16x32_bf16 v[96:99], v[166:169], v[190:193], v[96:99]
	v_mfma_f32_16x16x32_bf16 v[84:87], v[158:161], v[198:201], v[84:87]
	v_mfma_f32_16x16x32_bf16 v[80:83], v[166:169], v[198:201], v[80:83]
	v_mfma_f32_16x16x32_bf16 v[68:71], v[158:161], v[206:209], v[68:71]
	v_mfma_f32_16x16x32_bf16 v[64:67], v[166:169], v[206:209], v[64:67]
	v_mfma_f32_16x16x32_bf16 v[116:119], v[162:165], v[186:189], v[116:119]
	v_mfma_f32_16x16x32_bf16 v[112:115], v[170:173], v[186:189], v[112:115]
	v_mfma_f32_16x16x32_bf16 v[100:103], v[162:165], v[194:197], v[100:103]
	v_mfma_f32_16x16x32_bf16 v[96:99], v[170:173], v[194:197], v[96:99]
	v_mfma_f32_16x16x32_bf16 v[84:87], v[162:165], v[202:205], v[84:87]
	v_mfma_f32_16x16x32_bf16 v[80:83], v[170:173], v[202:205], v[80:83]
	v_mfma_f32_16x16x32_bf16 v[68:71], v[162:165], v[210:213], v[68:71]
	v_mfma_f32_16x16x32_bf16 v[64:67], v[170:173], v[210:213], v[64:67]
	s_barrier
	s_add_i32 s26, s61, s45
	v_lshl_add_u64 v[174:175], v[174:175], 0, s[72:73]
	s_mov_b32 m0, s26
	ds_read_b128 v[178:181], v145 offset:49152
	ds_read_b128 v[186:189], v145 offset:50176
	ds_read_b128 v[190:193], v145 offset:51200
	ds_read_b128 v[194:197], v145 offset:52224
	ds_read_b128 v[198:201], v145 offset:53248
	ds_read_b128 v[202:205], v145 offset:54272
	ds_read_b128 v[206:209], v145 offset:55296
	ds_read_b128 v[210:213], v145 offset:56320
	global_load_lds_dwordx4 v[174:175], off
	s_add_i32 m0, s26, 0x2000
	s_add_u32 s24, s24, 0x40080
	v_lshl_add_u64 v[174:175], v[182:183], 0, s[72:73]
	s_addc_u32 s25, s25, 0
	s_add_i32 s26, s62, s45
	global_load_lds_dwordx4 v[174:175], off
	v_lshl_add_u64 v[174:175], s[24:25], 0, v[176:177]
	s_mov_b32 m0, s26
	s_nop 0
	global_load_lds_dwordx4 v[174:175], off
	v_lshl_add_u64 v[174:175], s[24:25], 0, v[132:133]
	s_add_i32 m0, s26, 0x2000
	s_nop 0
	global_load_lds_dwordx4 v[174:175], off
	v_lshl_add_u64 v[174:175], v[184:185], 0, s[72:73]
	s_mov_b32 m0, s53
	s_nop 0
	global_load_lds_dwordx4 v[174:175], off
	v_lshl_add_u64 v[174:175], v[214:215], 0, s[72:73]
	s_mov_b32 m0, s56
	s_nop 0
	global_load_lds_dwordx4 v[174:175], off
	s_waitcnt vmcnt(8)
	s_waitcnt lgkmcnt(0)
	s_barrier
	s_waitcnt lgkmcnt(0)
	v_mfma_f32_16x16x32_bf16 v[60:63], v[138:141], v[178:181], v[60:63]
	v_mfma_f32_16x16x32_bf16 v[56:59], v[150:153], v[178:181], v[56:59]
	v_mfma_f32_16x16x32_bf16 v[44:47], v[138:141], v[190:193], v[44:47]
	v_mfma_f32_16x16x32_bf16 v[40:43], v[150:153], v[190:193], v[40:43]
	v_mfma_f32_16x16x32_bf16 v[28:31], v[138:141], v[198:201], v[28:31]
	v_mfma_f32_16x16x32_bf16 v[24:27], v[150:153], v[198:201], v[24:27]
	v_mfma_f32_16x16x32_bf16 v[12:15], v[138:141], v[206:209], v[12:15]
	v_mfma_f32_16x16x32_bf16 v[8:11], v[150:153], v[206:209], v[8:11]
	v_mfma_f32_16x16x32_bf16 v[60:63], v[146:149], v[186:189], v[60:63]
	v_mfma_f32_16x16x32_bf16 v[56:59], v[154:157], v[186:189], v[56:59]
	v_mfma_f32_16x16x32_bf16 v[44:47], v[146:149], v[194:197], v[44:47]
	v_mfma_f32_16x16x32_bf16 v[40:43], v[154:157], v[194:197], v[40:43]
	v_mfma_f32_16x16x32_bf16 v[28:31], v[146:149], v[202:205], v[28:31]
	v_mfma_f32_16x16x32_bf16 v[24:27], v[154:157], v[202:205], v[24:27]
	v_mfma_f32_16x16x32_bf16 v[12:15], v[146:149], v[210:213], v[12:15]
	v_mfma_f32_16x16x32_bf16 v[8:11], v[154:157], v[210:213], v[8:11]
	v_mfma_f32_16x16x32_bf16 v[52:55], v[158:161], v[178:181], v[52:55]
	v_mfma_f32_16x16x32_bf16 v[48:51], v[166:169], v[178:181], v[48:51]
	v_mfma_f32_16x16x32_bf16 v[36:39], v[158:161], v[190:193], v[36:39]
	v_mfma_f32_16x16x32_bf16 v[32:35], v[166:169], v[190:193], v[32:35]
	v_mfma_f32_16x16x32_bf16 v[20:23], v[158:161], v[198:201], v[20:23]
	v_mfma_f32_16x16x32_bf16 v[16:19], v[166:169], v[198:201], v[16:19]
	v_mfma_f32_16x16x32_bf16 v[4:7], v[158:161], v[206:209], v[4:7]
	v_mfma_f32_16x16x32_bf16 v[0:3], v[166:169], v[206:209], v[0:3]
	v_mfma_f32_16x16x32_bf16 v[52:55], v[162:165], v[186:189], v[52:55]
	v_mfma_f32_16x16x32_bf16 v[48:51], v[170:173], v[186:189], v[48:51]
	v_mfma_f32_16x16x32_bf16 v[36:39], v[162:165], v[194:197], v[36:39]
	v_mfma_f32_16x16x32_bf16 v[32:35], v[170:173], v[194:197], v[32:35]
	v_mfma_f32_16x16x32_bf16 v[20:23], v[162:165], v[202:205], v[20:23]
	v_mfma_f32_16x16x32_bf16 v[16:19], v[170:173], v[202:205], v[16:19]
	v_mfma_f32_16x16x32_bf16 v[4:7], v[162:165], v[210:213], v[4:7]
	v_mfma_f32_16x16x32_bf16 v[0:3], v[170:173], v[210:213], v[0:3]
	s_barrier
	s_add_i32 s60, s60, 2
	s_add_u32 s50, s50, 0x100
	s_addc_u32 s59, s59, 0
	s_add_u32 s22, s22, 0x100
	s_addc_u32 s23, s23, 0
	s_cmp_gt_u32 s60, 13
	s_cbranch_scc0 .LBB0_1472
	s_and_b64 vcc, exec, s[10:11]
	s_cbranch_vccz .LBB0_1475
	s_barrier

.LBB0_1614:
	s_add_u32 s36, s30, 0xfffe0080
	s_addc_u32 s37, s31, -1
	s_add_i32 s63, 0, 0x10000
	s_cmp_eq_u32 s62, 4
	s_cselect_b32 s39, s21, s37
	s_cselect_b32 s38, s27, s36
	s_cselect_b32 s37, s19, s50
	s_cselect_b32 s36, s42, s43
	s_add_i32 s66, 0, 0x14000
	v_add_u32_e32 v44, s63, v161
	v_add_u32_e32 v158, s66, v161
	ds_read_b128 v[24:27], v44
	ds_read_b128 v[28:31], v44 offset:1024
	ds_read_b128 v[40:43], v44 offset:2048
	ds_read_b128 v[44:47], v44 offset:3072
	ds_read_b128 v[154:157], v158
	ds_read_b128 v[164:167], v158 offset:1024
	ds_read_b128 v[168:171], v158 offset:2048
	ds_read_b128 v[172:175], v158 offset:3072
	v_lshl_add_u64 v[158:159], s[30:31], 0, v[152:153]
	s_add_i32 m0, s29, 0xc000
	ds_read_b128 v[178:181], v163
	ds_read_b128 v[186:189], v163 offset:1024
	ds_read_b128 v[190:193], v163 offset:2048
	ds_read_b128 v[194:197], v163 offset:3072
	ds_read_b128 v[198:201], v163 offset:4096
	ds_read_b128 v[202:205], v163 offset:5120
	ds_read_b128 v[206:209], v163 offset:6144
	ds_read_b128 v[210:213], v163 offset:7168
	global_load_lds_dwordx4 v[158:159], off
	v_lshl_add_u64 v[158:159], s[30:31], 0, v[150:151]
	s_add_i32 m0, s29, 0xe000
	s_nop 0
	global_load_lds_dwordx4 v[158:159], off
	s_waitcnt vmcnt(8)
	s_waitcnt lgkmcnt(0)
	s_barrier
	s_waitcnt lgkmcnt(0)
	v_mfma_f32_16x16x32_bf16 v[140:143], v[24:27], v[178:181], v[140:143]
	v_mfma_f32_16x16x32_bf16 v[136:139], v[40:43], v[178:181], v[136:139]
	v_mfma_f32_16x16x32_bf16 v[124:127], v[24:27], v[190:193], v[124:127]
	v_mfma_f32_16x16x32_bf16 v[120:123], v[40:43], v[190:193], v[120:123]
	v_mfma_f32_16x16x32_bf16 v[108:111], v[24:27], v[198:201], v[108:111]
	v_mfma_f32_16x16x32_bf16 v[104:107], v[40:43], v[198:201], v[104:107]
	v_mfma_f32_16x16x32_bf16 v[92:95], v[24:27], v[206:209], v[92:95]
	v_mfma_f32_16x16x32_bf16 v[88:91], v[40:43], v[206:209], v[88:91]
	v_mfma_f32_16x16x32_bf16 v[140:143], v[28:31], v[186:189], v[140:143]
	v_mfma_f32_16x16x32_bf16 v[136:139], v[44:47], v[186:189], v[136:139]
	v_mfma_f32_16x16x32_bf16 v[124:127], v[28:31], v[194:197], v[124:127]
	v_mfma_f32_16x16x32_bf16 v[120:123], v[44:47], v[194:197], v[120:123]
	v_mfma_f32_16x16x32_bf16 v[108:111], v[28:31], v[202:205], v[108:111]
	v_mfma_f32_16x16x32_bf16 v[104:107], v[44:47], v[202:205], v[104:107]
	v_mfma_f32_16x16x32_bf16 v[92:95], v[28:31], v[210:213], v[92:95]
	v_mfma_f32_16x16x32_bf16 v[88:91], v[44:47], v[210:213], v[88:91]
	v_mfma_f32_16x16x32_bf16 v[132:135], v[154:157], v[178:181], v[132:135]
	v_mfma_f32_16x16x32_bf16 v[128:131], v[168:171], v[178:181], v[128:131]
	v_mfma_f32_16x16x32_bf16 v[116:119], v[154:157], v[190:193], v[116:119]
	v_mfma_f32_16x16x32_bf16 v[112:115], v[168:171], v[190:193], v[112:115]
	v_mfma_f32_16x16x32_bf16 v[100:103], v[154:157], v[198:201], v[100:103]
	v_mfma_f32_16x16x32_bf16 v[96:99], v[168:171], v[198:201], v[96:99]
	v_mfma_f32_16x16x32_bf16 v[84:87], v[154:157], v[206:209], v[84:87]
	v_mfma_f32_16x16x32_bf16 v[80:83], v[168:171], v[206:209], v[80:83]
	v_mfma_f32_16x16x32_bf16 v[132:135], v[164:167], v[186:189], v[132:135]
	v_mfma_f32_16x16x32_bf16 v[128:131], v[172:175], v[186:189], v[128:131]
	v_mfma_f32_16x16x32_bf16 v[116:119], v[164:167], v[194:197], v[116:119]
	v_mfma_f32_16x16x32_bf16 v[112:115], v[172:175], v[194:197], v[112:115]
	v_mfma_f32_16x16x32_bf16 v[100:103], v[164:167], v[202:205], v[100:103]
	v_mfma_f32_16x16x32_bf16 v[96:99], v[172:175], v[202:205], v[96:99]
	v_mfma_f32_16x16x32_bf16 v[84:87], v[164:167], v[210:213], v[84:87]
	v_mfma_f32_16x16x32_bf16 v[80:83], v[172:175], v[210:213], v[80:83]
	s_barrier
	s_add_i32 s63, s63, s53
	v_lshl_add_u64 v[158:159], s[36:37], 0, v[176:177]
	s_mov_b32 m0, s63
	ds_read_b128 v[178:181], v163 offset:16384
	ds_read_b128 v[186:189], v163 offset:17408
	ds_read_b128 v[190:193], v163 offset:18432
	ds_read_b128 v[194:197], v163 offset:19456
	ds_read_b128 v[198:201], v163 offset:20480
	ds_read_b128 v[202:205], v163 offset:21504
	ds_read_b128 v[206:209], v163 offset:22528
	ds_read_b128 v[210:213], v163 offset:23552
	global_load_lds_dwordx4 v[158:159], off
	s_add_i32 m0, s63, 0x2000
	s_add_u32 s64, s36, 0x20000
	v_lshl_add_u64 v[182:183], s[36:37], 0, v[148:149]
	s_addc_u32 s65, s37, 0
	s_add_i32 s63, s66, s53
	global_load_lds_dwordx4 v[182:183], off
	v_lshl_add_u64 v[184:185], s[64:65], 0, v[176:177]
	s_mov_b32 m0, s63
	v_lshl_add_u64 v[214:215], s[38:39], 0, v[146:147]
	global_load_lds_dwordx4 v[184:185], off
	v_lshl_add_u64 v[184:185], s[64:65], 0, v[148:149]
	s_add_i32 m0, s63, 0x2000
	s_nop 0
	global_load_lds_dwordx4 v[184:185], off
	v_lshl_add_u64 v[184:185], s[38:39], 0, v[144:145]
	s_mov_b32 m0, s29
	s_nop 0
	global_load_lds_dwordx4 v[184:185], off
	s_mov_b32 m0, s56
	s_nop 0
	global_load_lds_dwordx4 v[214:215], off
	s_waitcnt vmcnt(8)
	s_waitcnt lgkmcnt(0)
	s_barrier
	s_waitcnt lgkmcnt(0)
	v_mfma_f32_16x16x32_bf16 v[76:79], v[24:27], v[178:181], v[76:79]
	v_mfma_f32_16x16x32_bf16 v[72:75], v[40:43], v[178:181], v[72:75]
	v_mfma_f32_16x16x32_bf16 v[60:63], v[24:27], v[190:193], v[60:63]
	v_mfma_f32_16x16x32_bf16 v[56:59], v[40:43], v[190:193], v[56:59]
	v_mfma_f32_16x16x32_bf16 v[36:39], v[24:27], v[198:201], v[36:39]
	v_mfma_f32_16x16x32_bf16 v[32:35], v[40:43], v[198:201], v[32:35]
	v_mfma_f32_16x16x32_bf16 v[12:15], v[24:27], v[206:209], v[12:15]
	v_mfma_f32_16x16x32_bf16 v[8:11], v[40:43], v[206:209], v[8:11]
	v_mfma_f32_16x16x32_bf16 v[76:79], v[28:31], v[186:189], v[76:79]
	v_mfma_f32_16x16x32_bf16 v[72:75], v[44:47], v[186:189], v[72:75]
	v_mfma_f32_16x16x32_bf16 v[60:63], v[28:31], v[194:197], v[60:63]
	v_mfma_f32_16x16x32_bf16 v[56:59], v[44:47], v[194:197], v[56:59]
	v_mfma_f32_16x16x32_bf16 v[36:39], v[28:31], v[202:205], v[36:39]
	v_mfma_f32_16x16x32_bf16 v[32:35], v[44:47], v[202:205], v[32:35]
	v_mfma_f32_16x16x32_bf16 v[12:15], v[28:31], v[210:213], v[12:15]
	v_mfma_f32_16x16x32_bf16 v[8:11], v[44:47], v[210:213], v[8:11]
	v_mfma_f32_16x16x32_bf16 v[20:23], v[154:157], v[198:201], v[20:23]
	v_mfma_f32_16x16x32_bf16 v[16:19], v[168:171], v[198:201], v[16:19]
	v_mfma_f32_16x16x32_bf16 v[4:7], v[154:157], v[206:209], v[4:7]
	v_mfma_f32_16x16x32_bf16 v[0:3], v[168:171], v[206:209], v[0:3]
	v_mfma_f32_16x16x32_bf16 v[24:27], v[154:157], v[178:181], v[68:71]
	v_mfma_f32_16x16x32_bf16 v[28:31], v[168:171], v[178:181], v[64:67]
	v_mfma_f32_16x16x32_bf16 v[40:43], v[154:157], v[190:193], v[52:55]
	v_mfma_f32_16x16x32_bf16 v[44:47], v[168:171], v[190:193], v[48:51]
	v_mfma_f32_16x16x32_bf16 v[20:23], v[164:167], v[202:205], v[20:23]
	v_mfma_f32_16x16x32_bf16 v[16:19], v[172:175], v[202:205], v[16:19]
	v_mfma_f32_16x16x32_bf16 v[4:7], v[164:167], v[210:213], v[4:7]
	v_mfma_f32_16x16x32_bf16 v[0:3], v[172:175], v[210:213], v[0:3]
	v_mfma_f32_16x16x32_bf16 v[24:27], v[164:167], v[186:189], v[24:27]
	v_mfma_f32_16x16x32_bf16 v[28:31], v[172:175], v[186:189], v[28:31]
	v_mfma_f32_16x16x32_bf16 v[40:43], v[164:167], v[194:197], v[40:43]
	v_mfma_f32_16x16x32_bf16 v[44:47], v[172:175], v[194:197], v[44:47]
	s_barrier
	s_add_i32 s63, 0, 0x18000
	s_add_i32 s64, 0, 0x1c000
	v_add_u32_e32 v68, s63, v161
	v_add_u32_e32 v172, s64, v161
	ds_read_b128 v[48:51], v68
	ds_read_b128 v[52:55], v68 offset:1024
	ds_read_b128 v[64:67], v68 offset:2048
	ds_read_b128 v[68:71], v68 offset:3072
	ds_read_b128 v[154:157], v172
	ds_read_b128 v[164:167], v172 offset:1024
	ds_read_b128 v[168:171], v172 offset:2048
	ds_read_b128 v[172:175], v172 offset:3072
	s_add_u32 s38, s38, 0x20000
	s_addc_u32 s39, s39, 0
	s_mov_b32 m0, s57
	v_lshl_add_u64 v[216:217], s[38:39], 0, v[144:145]
	ds_read_b128 v[178:181], v163 offset:32768
	ds_read_b128 v[186:189], v163 offset:33792
	ds_read_b128 v[190:193], v163 offset:34816
	ds_read_b128 v[194:197], v163 offset:35840
	ds_read_b128 v[198:201], v163 offset:36864
	ds_read_b128 v[202:205], v163 offset:37888
	ds_read_b128 v[206:209], v163 offset:38912
	ds_read_b128 v[210:213], v163 offset:39936
	global_load_lds_dwordx4 v[216:217], off
	v_lshl_add_u64 v[216:217], s[38:39], 0, v[146:147]
	s_mov_b32 m0, s58
	s_nop 0
	global_load_lds_dwordx4 v[216:217], off
	s_waitcnt vmcnt(8)
	s_waitcnt lgkmcnt(0)
	s_barrier
	s_waitcnt lgkmcnt(0)
	v_mfma_f32_16x16x32_bf16 v[140:143], v[48:51], v[178:181], v[140:143]
	v_mfma_f32_16x16x32_bf16 v[136:139], v[64:67], v[178:181], v[136:139]
	v_mfma_f32_16x16x32_bf16 v[124:127], v[48:51], v[190:193], v[124:127]
	v_mfma_f32_16x16x32_bf16 v[120:123], v[64:67], v[190:193], v[120:123]
	v_mfma_f32_16x16x32_bf16 v[108:111], v[48:51], v[198:201], v[108:111]
	v_mfma_f32_16x16x32_bf16 v[104:107], v[64:67], v[198:201], v[104:107]
	v_mfma_f32_16x16x32_bf16 v[92:95], v[48:51], v[206:209], v[92:95]
	v_mfma_f32_16x16x32_bf16 v[88:91], v[64:67], v[206:209], v[88:91]
	v_mfma_f32_16x16x32_bf16 v[140:143], v[52:55], v[186:189], v[140:143]
	v_mfma_f32_16x16x32_bf16 v[136:139], v[68:71], v[186:189], v[136:139]
	v_mfma_f32_16x16x32_bf16 v[124:127], v[52:55], v[194:197], v[124:127]
	v_mfma_f32_16x16x32_bf16 v[120:123], v[68:71], v[194:197], v[120:123]
	v_mfma_f32_16x16x32_bf16 v[108:111], v[52:55], v[202:205], v[108:111]
	v_mfma_f32_16x16x32_bf16 v[104:107], v[68:71], v[202:205], v[104:107]
	v_mfma_f32_16x16x32_bf16 v[92:95], v[52:55], v[210:213], v[92:95]
	v_mfma_f32_16x16x32_bf16 v[88:91], v[68:71], v[210:213], v[88:91]
	v_mfma_f32_16x16x32_bf16 v[132:135], v[154:157], v[178:181], v[132:135]
	v_mfma_f32_16x16x32_bf16 v[128:131], v[168:171], v[178:181], v[128:131]
	v_mfma_f32_16x16x32_bf16 v[116:119], v[154:157], v[190:193], v[116:119]
	v_mfma_f32_16x16x32_bf16 v[112:115], v[168:171], v[190:193], v[112:115]
	v_mfma_f32_16x16x32_bf16 v[100:103], v[154:157], v[198:201], v[100:103]
	v_mfma_f32_16x16x32_bf16 v[96:99], v[168:171], v[198:201], v[96:99]
	v_mfma_f32_16x16x32_bf16 v[84:87], v[154:157], v[206:209], v[84:87]
	v_mfma_f32_16x16x32_bf16 v[80:83], v[168:171], v[206:209], v[80:83]
	v_mfma_f32_16x16x32_bf16 v[132:135], v[164:167], v[186:189], v[132:135]
	v_mfma_f32_16x16x32_bf16 v[128:131], v[172:175], v[186:189], v[128:131]
	v_mfma_f32_16x16x32_bf16 v[116:119], v[164:167], v[194:197], v[116:119]
	v_mfma_f32_16x16x32_bf16 v[112:115], v[172:175], v[194:197], v[112:115]
	v_mfma_f32_16x16x32_bf16 v[100:103], v[164:167], v[202:205], v[100:103]
	v_mfma_f32_16x16x32_bf16 v[96:99], v[172:175], v[202:205], v[96:99]
	v_mfma_f32_16x16x32_bf16 v[84:87], v[164:167], v[210:213], v[84:87]
	v_mfma_f32_16x16x32_bf16 v[80:83], v[172:175], v[210:213], v[80:83]
	s_barrier
	s_add_i32 s38, s63, s53
	v_lshl_add_u64 v[158:159], v[158:159], 0, s[72:73]
	s_mov_b32 m0, s38
	ds_read_b128 v[178:181], v163 offset:49152
	ds_read_b128 v[186:189], v163 offset:50176
	ds_read_b128 v[190:193], v163 offset:51200
	ds_read_b128 v[194:197], v163 offset:52224
	ds_read_b128 v[198:201], v163 offset:53248
	ds_read_b128 v[202:205], v163 offset:54272
	ds_read_b128 v[206:209], v163 offset:55296
	ds_read_b128 v[210:213], v163 offset:56320
	global_load_lds_dwordx4 v[158:159], off
	s_add_i32 m0, s38, 0x2000
	s_add_u32 s36, s36, 0x20080
	v_lshl_add_u64 v[158:159], v[182:183], 0, s[72:73]
	s_addc_u32 s37, s37, 0
	s_add_i32 s38, s64, s53
	global_load_lds_dwordx4 v[158:159], off
	v_lshl_add_u64 v[158:159], s[36:37], 0, v[176:177]
	s_mov_b32 m0, s38
	s_nop 0
	global_load_lds_dwordx4 v[158:159], off
	v_lshl_add_u64 v[158:159], s[36:37], 0, v[148:149]
	s_add_i32 m0, s38, 0x2000
	s_nop 0
	global_load_lds_dwordx4 v[158:159], off
	v_lshl_add_u64 v[158:159], v[184:185], 0, s[72:73]
	s_mov_b32 m0, s40
	s_nop 0
	global_load_lds_dwordx4 v[158:159], off
	v_lshl_add_u64 v[158:159], v[214:215], 0, s[72:73]
	s_mov_b32 m0, s41
	s_nop 0
	global_load_lds_dwordx4 v[158:159], off
	s_waitcnt vmcnt(8)
	s_waitcnt lgkmcnt(0)
	s_barrier
	s_waitcnt lgkmcnt(0)
	v_mfma_f32_16x16x32_bf16 v[76:79], v[48:51], v[178:181], v[76:79]
	v_mfma_f32_16x16x32_bf16 v[72:75], v[64:67], v[178:181], v[72:75]
	v_mfma_f32_16x16x32_bf16 v[60:63], v[48:51], v[190:193], v[60:63]
	v_mfma_f32_16x16x32_bf16 v[56:59], v[64:67], v[190:193], v[56:59]
	v_mfma_f32_16x16x32_bf16 v[36:39], v[48:51], v[198:201], v[36:39]
	v_mfma_f32_16x16x32_bf16 v[32:35], v[64:67], v[198:201], v[32:35]
	v_mfma_f32_16x16x32_bf16 v[12:15], v[48:51], v[206:209], v[12:15]
	v_mfma_f32_16x16x32_bf16 v[8:11], v[64:67], v[206:209], v[8:11]
	v_mfma_f32_16x16x32_bf16 v[76:79], v[52:55], v[186:189], v[76:79]
	v_mfma_f32_16x16x32_bf16 v[72:75], v[68:71], v[186:189], v[72:75]
	v_mfma_f32_16x16x32_bf16 v[60:63], v[52:55], v[194:197], v[60:63]
	v_mfma_f32_16x16x32_bf16 v[56:59], v[68:71], v[194:197], v[56:59]
	v_mfma_f32_16x16x32_bf16 v[36:39], v[52:55], v[202:205], v[36:39]
	v_mfma_f32_16x16x32_bf16 v[32:35], v[68:71], v[202:205], v[32:35]
	v_mfma_f32_16x16x32_bf16 v[12:15], v[52:55], v[210:213], v[12:15]
	v_mfma_f32_16x16x32_bf16 v[8:11], v[68:71], v[210:213], v[8:11]
	v_mfma_f32_16x16x32_bf16 v[24:27], v[154:157], v[178:181], v[24:27]
	v_mfma_f32_16x16x32_bf16 v[68:71], v[164:167], v[186:189], v[24:27]
	v_mfma_f32_16x16x32_bf16 v[24:27], v[168:171], v[178:181], v[28:31]
	v_mfma_f32_16x16x32_bf16 v[64:67], v[172:175], v[186:189], v[24:27]
	v_mfma_f32_16x16x32_bf16 v[24:27], v[154:157], v[190:193], v[40:43]
	v_mfma_f32_16x16x32_bf16 v[52:55], v[164:167], v[194:197], v[24:27]
	v_mfma_f32_16x16x32_bf16 v[24:27], v[168:171], v[190:193], v[44:47]
	v_mfma_f32_16x16x32_bf16 v[20:23], v[154:157], v[198:201], v[20:23]
	v_mfma_f32_16x16x32_bf16 v[16:19], v[168:171], v[198:201], v[16:19]
	v_mfma_f32_16x16x32_bf16 v[4:7], v[154:157], v[206:209], v[4:7]
	v_mfma_f32_16x16x32_bf16 v[0:3], v[168:171], v[206:209], v[0:3]
	v_mfma_f32_16x16x32_bf16 v[48:51], v[172:175], v[194:197], v[24:27]
	v_mfma_f32_16x16x32_bf16 v[20:23], v[164:167], v[202:205], v[20:23]
	v_mfma_f32_16x16x32_bf16 v[16:19], v[172:175], v[202:205], v[16:19]
	v_mfma_f32_16x16x32_bf16 v[4:7], v[164:167], v[210:213], v[4:7]
	v_mfma_f32_16x16x32_bf16 v[0:3], v[172:175], v[210:213], v[0:3]
	s_barrier
	s_add_i32 s62, s62, 2
	s_add_u32 s43, s43, 0x100
	s_addc_u32 s50, s50, 0
	s_add_u32 s30, s30, 0x100
	s_addc_u32 s31, s31, 0
	s_cmp_gt_u32 s62, 5
	s_cbranch_scc0 .LBB0_1614
	s_and_b64 vcc, exec, s[16:17]
	s_cbranch_vccz .LBB0_1617
	s_barrier

.LBB0_1694:
	s_add_u32 s10, s8, 0xfffc0080
	s_addc_u32 s11, s9, -1
	s_add_i32 s19, 0, 0x10000
	s_cmp_eq_u32 s18, 12
	s_cselect_b32 s13, s5, s11
	s_cselect_b32 s12, s7, s10
	s_cselect_b32 s11, s14, s17
	s_cselect_b32 s10, s15, s16
	s_add_i32 s22, 0, 0x14000
	v_add_u32_e32 v140, s19, v203
	v_add_u32_e32 v156, s22, v203
	ds_read_b128 v[128:131], v140
	ds_read_b128 v[132:135], v140 offset:1024
	ds_read_b128 v[136:139], v140 offset:2048
	ds_read_b128 v[140:143], v140 offset:3072
	ds_read_b128 v[144:147], v156
	ds_read_b128 v[148:151], v156 offset:1024
	ds_read_b128 v[152:155], v156 offset:2048
	ds_read_b128 v[156:159], v156 offset:3072
	v_lshl_add_u64 v[174:175], s[8:9], 0, v[168:169]
	s_add_i32 m0, s61, 0xc000
	ds_read_b128 v[170:173], v207
	ds_read_b128 v[178:181], v207 offset:1024
	ds_read_b128 v[188:191], v207 offset:2048
	ds_read_b128 v[192:195], v207 offset:3072
	ds_read_b128 v[196:199], v207 offset:4096
	ds_read_b128 v[208:211], v207 offset:5120
	ds_read_b128 v[212:215], v207 offset:6144
	ds_read_b128 v[216:219], v207 offset:7168
	global_load_lds_dwordx4 v[174:175], off
	v_lshl_add_u64 v[174:175], s[8:9], 0, v[166:167]
	s_add_i32 m0, s61, 0xe000
	s_nop 0
	global_load_lds_dwordx4 v[174:175], off
	s_waitcnt vmcnt(8)
	s_waitcnt lgkmcnt(0)
	s_barrier
	s_waitcnt lgkmcnt(0)
	v_mfma_f32_16x16x32_bf16 v[124:127], v[128:131], v[170:173], v[124:127]
	v_mfma_f32_16x16x32_bf16 v[92:95], v[136:139], v[170:173], v[92:95]
	v_mfma_f32_16x16x32_bf16 v[116:119], v[128:131], v[188:191], v[116:119]
	v_mfma_f32_16x16x32_bf16 v[84:87], v[136:139], v[188:191], v[84:87]
	v_mfma_f32_16x16x32_bf16 v[108:111], v[128:131], v[196:199], v[108:111]
	v_mfma_f32_16x16x32_bf16 v[76:79], v[136:139], v[196:199], v[76:79]
	v_mfma_f32_16x16x32_bf16 v[100:103], v[128:131], v[212:215], v[100:103]
	v_mfma_f32_16x16x32_bf16 v[68:71], v[136:139], v[212:215], v[68:71]
	v_mfma_f32_16x16x32_bf16 v[124:127], v[132:135], v[178:181], v[124:127]
	v_mfma_f32_16x16x32_bf16 v[92:95], v[140:143], v[178:181], v[92:95]
	v_mfma_f32_16x16x32_bf16 v[116:119], v[132:135], v[192:195], v[116:119]
	v_mfma_f32_16x16x32_bf16 v[84:87], v[140:143], v[192:195], v[84:87]
	v_mfma_f32_16x16x32_bf16 v[108:111], v[132:135], v[208:211], v[108:111]
	v_mfma_f32_16x16x32_bf16 v[76:79], v[140:143], v[208:211], v[76:79]
	v_mfma_f32_16x16x32_bf16 v[100:103], v[132:135], v[216:219], v[100:103]
	v_mfma_f32_16x16x32_bf16 v[68:71], v[140:143], v[216:219], v[68:71]
	v_mfma_f32_16x16x32_bf16 v[120:123], v[144:147], v[170:173], v[120:123]
	v_mfma_f32_16x16x32_bf16 v[88:91], v[152:155], v[170:173], v[88:91]
	v_mfma_f32_16x16x32_bf16 v[112:115], v[144:147], v[188:191], v[112:115]
	v_mfma_f32_16x16x32_bf16 v[80:83], v[152:155], v[188:191], v[80:83]
	v_mfma_f32_16x16x32_bf16 v[104:107], v[144:147], v[196:199], v[104:107]
	v_mfma_f32_16x16x32_bf16 v[72:75], v[152:155], v[196:199], v[72:75]
	v_mfma_f32_16x16x32_bf16 v[96:99], v[144:147], v[212:215], v[96:99]
	v_mfma_f32_16x16x32_bf16 v[64:67], v[152:155], v[212:215], v[64:67]
	v_mfma_f32_16x16x32_bf16 v[120:123], v[148:151], v[178:181], v[120:123]
	v_mfma_f32_16x16x32_bf16 v[88:91], v[156:159], v[178:181], v[88:91]
	v_mfma_f32_16x16x32_bf16 v[112:115], v[148:151], v[192:195], v[112:115]
	v_mfma_f32_16x16x32_bf16 v[80:83], v[156:159], v[192:195], v[80:83]
	v_mfma_f32_16x16x32_bf16 v[104:107], v[148:151], v[208:211], v[104:107]
	v_mfma_f32_16x16x32_bf16 v[72:75], v[156:159], v[208:211], v[72:75]
	v_mfma_f32_16x16x32_bf16 v[96:99], v[148:151], v[216:219], v[96:99]
	v_mfma_f32_16x16x32_bf16 v[64:67], v[156:159], v[216:219], v[64:67]
	s_barrier
	s_add_i32 s19, s19, s60
	v_lshl_add_u64 v[174:175], s[10:11], 0, v[176:177]
	s_mov_b32 m0, s19
	ds_read_b128 v[170:173], v207 offset:16384
	ds_read_b128 v[178:181], v207 offset:17408
	ds_read_b128 v[188:191], v207 offset:18432
	ds_read_b128 v[192:195], v207 offset:19456
	ds_read_b128 v[196:199], v207 offset:20480
	ds_read_b128 v[208:211], v207 offset:21504
	ds_read_b128 v[212:215], v207 offset:22528
	ds_read_b128 v[216:219], v207 offset:23552
	global_load_lds_dwordx4 v[174:175], off
	s_add_i32 m0, s19, 0x2000
	s_add_u32 s20, s10, 0x40000
	v_lshl_add_u64 v[182:183], s[10:11], 0, v[164:165]
	s_addc_u32 s21, s11, 0
	s_add_i32 s19, s22, s60
	global_load_lds_dwordx4 v[182:183], off
	v_lshl_add_u64 v[184:185], s[20:21], 0, v[176:177]
	s_mov_b32 m0, s19
	v_lshl_add_u64 v[204:205], s[12:13], 0, v[162:163]
	global_load_lds_dwordx4 v[184:185], off
	v_lshl_add_u64 v[184:185], s[20:21], 0, v[164:165]
	s_add_i32 m0, s19, 0x2000
	s_nop 0
	global_load_lds_dwordx4 v[184:185], off
	v_lshl_add_u64 v[184:185], s[12:13], 0, v[160:161]
	s_mov_b32 m0, s61
	s_nop 0
	global_load_lds_dwordx4 v[184:185], off
	s_mov_b32 m0, s62
	s_nop 0
	global_load_lds_dwordx4 v[204:205], off
	s_waitcnt vmcnt(8)
	s_waitcnt lgkmcnt(0)
	s_barrier
	s_waitcnt lgkmcnt(0)
	v_mfma_f32_16x16x32_bf16 v[60:63], v[128:131], v[170:173], v[60:63]
	v_mfma_f32_16x16x32_bf16 v[28:31], v[136:139], v[170:173], v[28:31]
	v_mfma_f32_16x16x32_bf16 v[52:55], v[128:131], v[188:191], v[52:55]
	v_mfma_f32_16x16x32_bf16 v[20:23], v[136:139], v[188:191], v[20:23]
	v_mfma_f32_16x16x32_bf16 v[44:47], v[128:131], v[196:199], v[44:47]
	v_mfma_f32_16x16x32_bf16 v[12:15], v[136:139], v[196:199], v[12:15]
	v_mfma_f32_16x16x32_bf16 v[36:39], v[128:131], v[212:215], v[36:39]
	v_mfma_f32_16x16x32_bf16 v[4:7], v[136:139], v[212:215], v[4:7]
	v_mfma_f32_16x16x32_bf16 v[60:63], v[132:135], v[178:181], v[60:63]
	v_mfma_f32_16x16x32_bf16 v[28:31], v[140:143], v[178:181], v[28:31]
	v_mfma_f32_16x16x32_bf16 v[52:55], v[132:135], v[192:195], v[52:55]
	v_mfma_f32_16x16x32_bf16 v[20:23], v[140:143], v[192:195], v[20:23]
	v_mfma_f32_16x16x32_bf16 v[44:47], v[132:135], v[208:211], v[44:47]
	v_mfma_f32_16x16x32_bf16 v[12:15], v[140:143], v[208:211], v[12:15]
	v_mfma_f32_16x16x32_bf16 v[36:39], v[132:135], v[216:219], v[36:39]
	v_mfma_f32_16x16x32_bf16 v[4:7], v[140:143], v[216:219], v[4:7]
	v_mfma_f32_16x16x32_bf16 v[56:59], v[144:147], v[170:173], v[56:59]
	v_mfma_f32_16x16x32_bf16 v[24:27], v[152:155], v[170:173], v[24:27]
	v_mfma_f32_16x16x32_bf16 v[48:51], v[144:147], v[188:191], v[48:51]
	v_mfma_f32_16x16x32_bf16 v[16:19], v[152:155], v[188:191], v[16:19]
	v_mfma_f32_16x16x32_bf16 v[40:43], v[144:147], v[196:199], v[40:43]
	v_mfma_f32_16x16x32_bf16 v[8:11], v[152:155], v[196:199], v[8:11]
	v_mfma_f32_16x16x32_bf16 v[32:35], v[144:147], v[212:215], v[32:35]
	v_mfma_f32_16x16x32_bf16 v[0:3], v[152:155], v[212:215], v[0:3]
	v_mfma_f32_16x16x32_bf16 v[56:59], v[148:151], v[178:181], v[56:59]
	v_mfma_f32_16x16x32_bf16 v[24:27], v[156:159], v[178:181], v[24:27]
	v_mfma_f32_16x16x32_bf16 v[48:51], v[148:151], v[192:195], v[48:51]
	v_mfma_f32_16x16x32_bf16 v[16:19], v[156:159], v[192:195], v[16:19]
	v_mfma_f32_16x16x32_bf16 v[40:43], v[148:151], v[208:211], v[40:43]
	v_mfma_f32_16x16x32_bf16 v[8:11], v[156:159], v[208:211], v[8:11]
	v_mfma_f32_16x16x32_bf16 v[32:35], v[148:151], v[216:219], v[32:35]
	v_mfma_f32_16x16x32_bf16 v[0:3], v[156:159], v[216:219], v[0:3]
	s_barrier
	s_add_i32 s19, 0, 0x18000
	s_add_i32 s20, 0, 0x1c000
	v_add_u32_e32 v140, s19, v203
	v_add_u32_e32 v156, s20, v203
	ds_read_b128 v[128:131], v140
	ds_read_b128 v[132:135], v140 offset:1024
	ds_read_b128 v[136:139], v140 offset:2048
	ds_read_b128 v[140:143], v140 offset:3072
	ds_read_b128 v[144:147], v156
	ds_read_b128 v[148:151], v156 offset:1024
	ds_read_b128 v[152:155], v156 offset:2048
	ds_read_b128 v[156:159], v156 offset:3072
	s_add_u32 s12, s12, 0x40000
	s_addc_u32 s13, s13, 0
	s_mov_b32 m0, s63
	v_lshl_add_u64 v[222:223], s[12:13], 0, v[160:161]
	ds_read_b128 v[170:173], v207 offset:32768
	ds_read_b128 v[178:181], v207 offset:33792
	ds_read_b128 v[188:191], v207 offset:34816
	ds_read_b128 v[192:195], v207 offset:35840
	ds_read_b128 v[196:199], v207 offset:36864
	ds_read_b128 v[208:211], v207 offset:37888
	ds_read_b128 v[212:215], v207 offset:38912
	ds_read_b128 v[216:219], v207 offset:39936
	global_load_lds_dwordx4 v[222:223], off
	v_lshl_add_u64 v[222:223], s[12:13], 0, v[162:163]
	s_mov_b32 m0, s66
	s_nop 0
	global_load_lds_dwordx4 v[222:223], off
	s_waitcnt vmcnt(8)
	s_waitcnt lgkmcnt(0)
	s_barrier
	s_waitcnt lgkmcnt(0)
	v_mfma_f32_16x16x32_bf16 v[124:127], v[128:131], v[170:173], v[124:127]
	v_mfma_f32_16x16x32_bf16 v[92:95], v[136:139], v[170:173], v[92:95]
	v_mfma_f32_16x16x32_bf16 v[116:119], v[128:131], v[188:191], v[116:119]
	v_mfma_f32_16x16x32_bf16 v[84:87], v[136:139], v[188:191], v[84:87]
	v_mfma_f32_16x16x32_bf16 v[108:111], v[128:131], v[196:199], v[108:111]
	v_mfma_f32_16x16x32_bf16 v[76:79], v[136:139], v[196:199], v[76:79]
	v_mfma_f32_16x16x32_bf16 v[100:103], v[128:131], v[212:215], v[100:103]
	v_mfma_f32_16x16x32_bf16 v[68:71], v[136:139], v[212:215], v[68:71]
	v_mfma_f32_16x16x32_bf16 v[124:127], v[132:135], v[178:181], v[124:127]
	v_mfma_f32_16x16x32_bf16 v[92:95], v[140:143], v[178:181], v[92:95]
	v_mfma_f32_16x16x32_bf16 v[116:119], v[132:135], v[192:195], v[116:119]
	v_mfma_f32_16x16x32_bf16 v[84:87], v[140:143], v[192:195], v[84:87]
	v_mfma_f32_16x16x32_bf16 v[108:111], v[132:135], v[208:211], v[108:111]
	v_mfma_f32_16x16x32_bf16 v[76:79], v[140:143], v[208:211], v[76:79]
	v_mfma_f32_16x16x32_bf16 v[100:103], v[132:135], v[216:219], v[100:103]
	v_mfma_f32_16x16x32_bf16 v[68:71], v[140:143], v[216:219], v[68:71]
	v_mfma_f32_16x16x32_bf16 v[120:123], v[144:147], v[170:173], v[120:123]
	v_mfma_f32_16x16x32_bf16 v[88:91], v[152:155], v[170:173], v[88:91]
	v_mfma_f32_16x16x32_bf16 v[112:115], v[144:147], v[188:191], v[112:115]
	v_mfma_f32_16x16x32_bf16 v[80:83], v[152:155], v[188:191], v[80:83]
	v_mfma_f32_16x16x32_bf16 v[104:107], v[144:147], v[196:199], v[104:107]
	v_mfma_f32_16x16x32_bf16 v[72:75], v[152:155], v[196:199], v[72:75]
	v_mfma_f32_16x16x32_bf16 v[96:99], v[144:147], v[212:215], v[96:99]
	v_mfma_f32_16x16x32_bf16 v[64:67], v[152:155], v[212:215], v[64:67]
	v_mfma_f32_16x16x32_bf16 v[120:123], v[148:151], v[178:181], v[120:123]
	v_mfma_f32_16x16x32_bf16 v[88:91], v[156:159], v[178:181], v[88:91]
	v_mfma_f32_16x16x32_bf16 v[112:115], v[148:151], v[192:195], v[112:115]
	v_mfma_f32_16x16x32_bf16 v[80:83], v[156:159], v[192:195], v[80:83]
	v_mfma_f32_16x16x32_bf16 v[104:107], v[148:151], v[208:211], v[104:107]
	v_mfma_f32_16x16x32_bf16 v[72:75], v[156:159], v[208:211], v[72:75]
	v_mfma_f32_16x16x32_bf16 v[96:99], v[148:151], v[216:219], v[96:99]
	v_mfma_f32_16x16x32_bf16 v[64:67], v[156:159], v[216:219], v[64:67]
	s_barrier
	s_add_i32 s12, s19, s60
	v_lshl_add_u64 v[174:175], v[174:175], 0, s[72:73]
	s_mov_b32 m0, s12
	ds_read_b128 v[170:173], v207 offset:49152
	ds_read_b128 v[178:181], v207 offset:50176
	ds_read_b128 v[188:191], v207 offset:51200
	ds_read_b128 v[192:195], v207 offset:52224
	ds_read_b128 v[196:199], v207 offset:53248
	ds_read_b128 v[208:211], v207 offset:54272
	ds_read_b128 v[212:215], v207 offset:55296
	ds_read_b128 v[216:219], v207 offset:56320
	global_load_lds_dwordx4 v[174:175], off
	s_add_i32 m0, s12, 0x2000
	s_add_u32 s10, s10, 0x40080
	v_lshl_add_u64 v[174:175], v[182:183], 0, s[72:73]
	s_addc_u32 s11, s11, 0
	s_add_i32 s12, s20, s60
	global_load_lds_dwordx4 v[174:175], off
	v_lshl_add_u64 v[174:175], s[10:11], 0, v[176:177]
	s_mov_b32 m0, s12
	s_nop 0
	global_load_lds_dwordx4 v[174:175], off
	v_lshl_add_u64 v[174:175], s[10:11], 0, v[164:165]
	s_add_i32 m0, s12, 0x2000
	s_nop 0
	global_load_lds_dwordx4 v[174:175], off
	v_lshl_add_u64 v[174:175], v[184:185], 0, s[72:73]
	s_mov_b32 m0, s69
	s_nop 0
	global_load_lds_dwordx4 v[174:175], off
	v_lshl_add_u64 v[174:175], v[204:205], 0, s[72:73]
	s_mov_b32 m0, s77
	s_nop 0
	global_load_lds_dwordx4 v[174:175], off
	s_waitcnt vmcnt(8)
	s_waitcnt lgkmcnt(0)
	s_barrier
	s_waitcnt lgkmcnt(0)
	v_mfma_f32_16x16x32_bf16 v[60:63], v[128:131], v[170:173], v[60:63]
	v_mfma_f32_16x16x32_bf16 v[28:31], v[136:139], v[170:173], v[28:31]
	v_mfma_f32_16x16x32_bf16 v[52:55], v[128:131], v[188:191], v[52:55]
	v_mfma_f32_16x16x32_bf16 v[20:23], v[136:139], v[188:191], v[20:23]
	v_mfma_f32_16x16x32_bf16 v[44:47], v[128:131], v[196:199], v[44:47]
	v_mfma_f32_16x16x32_bf16 v[12:15], v[136:139], v[196:199], v[12:15]
	v_mfma_f32_16x16x32_bf16 v[36:39], v[128:131], v[212:215], v[36:39]
	v_mfma_f32_16x16x32_bf16 v[4:7], v[136:139], v[212:215], v[4:7]
	v_mfma_f32_16x16x32_bf16 v[60:63], v[132:135], v[178:181], v[60:63]
	v_mfma_f32_16x16x32_bf16 v[28:31], v[140:143], v[178:181], v[28:31]
	v_mfma_f32_16x16x32_bf16 v[52:55], v[132:135], v[192:195], v[52:55]
	v_mfma_f32_16x16x32_bf16 v[20:23], v[140:143], v[192:195], v[20:23]
	v_mfma_f32_16x16x32_bf16 v[44:47], v[132:135], v[208:211], v[44:47]
	v_mfma_f32_16x16x32_bf16 v[12:15], v[140:143], v[208:211], v[12:15]
	v_mfma_f32_16x16x32_bf16 v[36:39], v[132:135], v[216:219], v[36:39]
	v_mfma_f32_16x16x32_bf16 v[4:7], v[140:143], v[216:219], v[4:7]
	v_mfma_f32_16x16x32_bf16 v[56:59], v[144:147], v[170:173], v[56:59]
	v_mfma_f32_16x16x32_bf16 v[24:27], v[152:155], v[170:173], v[24:27]
	v_mfma_f32_16x16x32_bf16 v[48:51], v[144:147], v[188:191], v[48:51]
	v_mfma_f32_16x16x32_bf16 v[16:19], v[152:155], v[188:191], v[16:19]
	v_mfma_f32_16x16x32_bf16 v[40:43], v[144:147], v[196:199], v[40:43]
	v_mfma_f32_16x16x32_bf16 v[8:11], v[152:155], v[196:199], v[8:11]
	v_mfma_f32_16x16x32_bf16 v[32:35], v[144:147], v[212:215], v[32:35]
	v_mfma_f32_16x16x32_bf16 v[0:3], v[152:155], v[212:215], v[0:3]
	v_mfma_f32_16x16x32_bf16 v[56:59], v[148:151], v[178:181], v[56:59]
	v_mfma_f32_16x16x32_bf16 v[24:27], v[156:159], v[178:181], v[24:27]
	v_mfma_f32_16x16x32_bf16 v[48:51], v[148:151], v[192:195], v[48:51]
	v_mfma_f32_16x16x32_bf16 v[16:19], v[156:159], v[192:195], v[16:19]
	v_mfma_f32_16x16x32_bf16 v[40:43], v[148:151], v[208:211], v[40:43]
	v_mfma_f32_16x16x32_bf16 v[8:11], v[156:159], v[208:211], v[8:11]
	v_mfma_f32_16x16x32_bf16 v[32:35], v[148:151], v[216:219], v[32:35]
	v_mfma_f32_16x16x32_bf16 v[0:3], v[156:159], v[216:219], v[0:3]
	s_barrier
	s_add_i32 s18, s18, 2
	s_add_u32 s16, s16, 0x100
	s_addc_u32 s17, s17, 0
	s_add_u32 s8, s8, 0x100
	s_addc_u32 s9, s9, 0
	s_cmp_gt_u32 s18, 13
	s_cbranch_scc0 .LBB0_1694
	s_and_b64 vcc, exec, s[80:81]
	s_cbranch_vccz .LBB0_1697
	s_barrier

.LBB0_1901:
	s_add_u32 s6, s8, 0x100
	s_addc_u32 s7, s9, 0
	s_add_i32 s59, 0, 0x10000
	s_cmp_eq_u32 s58, 40
	s_cselect_b32 s31, s25, s7
	s_cselect_b32 s30, s24, s6
	s_cselect_b32 s29, s27, s57
	s_cselect_b32 s28, s26, s50
	s_add_i32 s60, 0, 0x14000
	v_add_u32_e32 v68, s59, v167
	v_add_u32_e32 v170, s60, v167
	ds_read_b128 v[48:51], v68
	ds_read_b128 v[52:55], v68 offset:1024
	ds_read_b128 v[64:67], v68 offset:2048
	ds_read_b128 v[68:71], v68 offset:3072
	ds_read_b128 v[154:157], v170
	ds_read_b128 v[158:161], v170 offset:1024
	ds_read_b128 v[162:165], v170 offset:2048
	ds_read_b128 v[170:173], v170 offset:3072
	v_lshl_add_u64 v[174:175], s[8:9], 0, v[152:153]
	s_add_i32 m0, s41, 0xc000
	ds_read_b128 v[178:181], v169
	ds_read_b128 v[186:189], v169 offset:1024
	ds_read_b128 v[190:193], v169 offset:2048
	ds_read_b128 v[194:197], v169 offset:3072
	ds_read_b128 v[198:201], v169 offset:4096
	ds_read_b128 v[202:205], v169 offset:5120
	ds_read_b128 v[206:209], v169 offset:6144
	ds_read_b128 v[210:213], v169 offset:7168
	global_load_lds_dwordx4 v[174:175], off
	v_lshl_add_u64 v[174:175], s[8:9], 0, v[150:151]
	s_add_i32 m0, s41, 0xe000
	s_nop 0
	global_load_lds_dwordx4 v[174:175], off
	s_waitcnt vmcnt(8)
	s_waitcnt lgkmcnt(0)
	s_barrier
	s_waitcnt lgkmcnt(0)
	v_mfma_f32_16x16x32_bf16 v[140:143], v[48:51], v[178:181], v[140:143]
	v_mfma_f32_16x16x32_bf16 v[136:139], v[64:67], v[178:181], v[136:139]
	v_mfma_f32_16x16x32_bf16 v[124:127], v[48:51], v[190:193], v[124:127]
	v_mfma_f32_16x16x32_bf16 v[120:123], v[64:67], v[190:193], v[120:123]
	v_mfma_f32_16x16x32_bf16 v[108:111], v[48:51], v[198:201], v[108:111]
	v_mfma_f32_16x16x32_bf16 v[104:107], v[64:67], v[198:201], v[104:107]
	v_mfma_f32_16x16x32_bf16 v[92:95], v[48:51], v[206:209], v[92:95]
	v_mfma_f32_16x16x32_bf16 v[88:91], v[64:67], v[206:209], v[88:91]
	v_mfma_f32_16x16x32_bf16 v[140:143], v[52:55], v[186:189], v[140:143]
	v_mfma_f32_16x16x32_bf16 v[136:139], v[68:71], v[186:189], v[136:139]
	v_mfma_f32_16x16x32_bf16 v[124:127], v[52:55], v[194:197], v[124:127]
	v_mfma_f32_16x16x32_bf16 v[120:123], v[68:71], v[194:197], v[120:123]
	v_mfma_f32_16x16x32_bf16 v[108:111], v[52:55], v[202:205], v[108:111]
	v_mfma_f32_16x16x32_bf16 v[104:107], v[68:71], v[202:205], v[104:107]
	v_mfma_f32_16x16x32_bf16 v[92:95], v[52:55], v[210:213], v[92:95]
	v_mfma_f32_16x16x32_bf16 v[88:91], v[68:71], v[210:213], v[88:91]
	v_mfma_f32_16x16x32_bf16 v[132:135], v[154:157], v[178:181], v[132:135]
	v_mfma_f32_16x16x32_bf16 v[128:131], v[162:165], v[178:181], v[128:131]
	v_mfma_f32_16x16x32_bf16 v[116:119], v[154:157], v[190:193], v[116:119]
	v_mfma_f32_16x16x32_bf16 v[112:115], v[162:165], v[190:193], v[112:115]
	v_mfma_f32_16x16x32_bf16 v[100:103], v[154:157], v[198:201], v[100:103]
	v_mfma_f32_16x16x32_bf16 v[96:99], v[162:165], v[198:201], v[96:99]
	v_mfma_f32_16x16x32_bf16 v[84:87], v[154:157], v[206:209], v[84:87]
	v_mfma_f32_16x16x32_bf16 v[80:83], v[162:165], v[206:209], v[80:83]
	v_mfma_f32_16x16x32_bf16 v[132:135], v[158:161], v[186:189], v[132:135]
	v_mfma_f32_16x16x32_bf16 v[128:131], v[170:173], v[186:189], v[128:131]
	v_mfma_f32_16x16x32_bf16 v[116:119], v[158:161], v[194:197], v[116:119]
	v_mfma_f32_16x16x32_bf16 v[112:115], v[170:173], v[194:197], v[112:115]
	v_mfma_f32_16x16x32_bf16 v[100:103], v[158:161], v[202:205], v[100:103]
	v_mfma_f32_16x16x32_bf16 v[96:99], v[170:173], v[202:205], v[96:99]
	v_mfma_f32_16x16x32_bf16 v[84:87], v[158:161], v[210:213], v[84:87]
	v_mfma_f32_16x16x32_bf16 v[80:83], v[170:173], v[210:213], v[80:83]
	s_barrier
	s_add_i32 s8, s59, s40
	v_lshl_add_u64 v[174:175], s[28:29], 0, v[176:177]
	s_mov_b32 m0, s8
	ds_read_b128 v[178:181], v169 offset:16384
	ds_read_b128 v[186:189], v169 offset:17408
	ds_read_b128 v[190:193], v169 offset:18432
	ds_read_b128 v[194:197], v169 offset:19456
	ds_read_b128 v[198:201], v169 offset:20480
	ds_read_b128 v[202:205], v169 offset:21504
	ds_read_b128 v[206:209], v169 offset:22528
	ds_read_b128 v[210:213], v169 offset:23552
	global_load_lds_dwordx4 v[174:175], off
	s_add_i32 m0, s8, 0x2000
	s_add_u32 s8, s28, 0xb0000
	v_lshl_add_u64 v[182:183], s[28:29], 0, v[148:149]
	s_addc_u32 s9, s29, 0
	s_add_i32 s59, s60, s40
	global_load_lds_dwordx4 v[182:183], off
	v_lshl_add_u64 v[184:185], s[8:9], 0, v[176:177]
	s_mov_b32 m0, s59
	v_lshl_add_u64 v[214:215], s[30:31], 0, v[146:147]
	global_load_lds_dwordx4 v[184:185], off
	v_lshl_add_u64 v[184:185], s[8:9], 0, v[148:149]
	s_add_i32 m0, s59, 0x2000
	s_nop 0
	global_load_lds_dwordx4 v[184:185], off
	v_lshl_add_u64 v[184:185], s[30:31], 0, v[144:145]
	s_mov_b32 m0, s41
	s_nop 0
	global_load_lds_dwordx4 v[184:185], off
	s_mov_b32 m0, s44
	s_nop 0
	global_load_lds_dwordx4 v[214:215], off
	s_waitcnt vmcnt(8)
	s_waitcnt lgkmcnt(0)
	s_barrier
	s_waitcnt lgkmcnt(0)
	v_mfma_f32_16x16x32_bf16 v[76:79], v[48:51], v[178:181], v[76:79]
	v_mfma_f32_16x16x32_bf16 v[72:75], v[64:67], v[178:181], v[72:75]
	v_mfma_f32_16x16x32_bf16 v[44:47], v[48:51], v[190:193], v[44:47]
	v_mfma_f32_16x16x32_bf16 v[40:43], v[64:67], v[190:193], v[40:43]
	v_mfma_f32_16x16x32_bf16 v[28:31], v[48:51], v[198:201], v[28:31]
	v_mfma_f32_16x16x32_bf16 v[24:27], v[64:67], v[198:201], v[24:27]
	v_mfma_f32_16x16x32_bf16 v[12:15], v[48:51], v[206:209], v[12:15]
	v_mfma_f32_16x16x32_bf16 v[8:11], v[64:67], v[206:209], v[8:11]
	v_mfma_f32_16x16x32_bf16 v[76:79], v[52:55], v[186:189], v[76:79]
	v_mfma_f32_16x16x32_bf16 v[72:75], v[68:71], v[186:189], v[72:75]
	v_mfma_f32_16x16x32_bf16 v[44:47], v[52:55], v[194:197], v[44:47]
	v_mfma_f32_16x16x32_bf16 v[40:43], v[68:71], v[194:197], v[40:43]
	v_mfma_f32_16x16x32_bf16 v[28:31], v[52:55], v[202:205], v[28:31]
	v_mfma_f32_16x16x32_bf16 v[24:27], v[68:71], v[202:205], v[24:27]
	v_mfma_f32_16x16x32_bf16 v[12:15], v[52:55], v[210:213], v[12:15]
	v_mfma_f32_16x16x32_bf16 v[8:11], v[68:71], v[210:213], v[8:11]
	v_mfma_f32_16x16x32_bf16 v[36:39], v[154:157], v[190:193], v[36:39]
	v_mfma_f32_16x16x32_bf16 v[32:35], v[162:165], v[190:193], v[32:35]
	v_mfma_f32_16x16x32_bf16 v[20:23], v[154:157], v[198:201], v[20:23]
	v_mfma_f32_16x16x32_bf16 v[16:19], v[162:165], v[198:201], v[16:19]
	v_mfma_f32_16x16x32_bf16 v[4:7], v[154:157], v[206:209], v[4:7]
	v_mfma_f32_16x16x32_bf16 v[0:3], v[162:165], v[206:209], v[0:3]
	v_mfma_f32_16x16x32_bf16 v[48:51], v[154:157], v[178:181], v[60:63]
	v_mfma_f32_16x16x32_bf16 v[52:55], v[162:165], v[178:181], v[56:59]
	v_mfma_f32_16x16x32_bf16 v[36:39], v[158:161], v[194:197], v[36:39]
	v_mfma_f32_16x16x32_bf16 v[32:35], v[170:173], v[194:197], v[32:35]
	v_mfma_f32_16x16x32_bf16 v[20:23], v[158:161], v[202:205], v[20:23]
	v_mfma_f32_16x16x32_bf16 v[16:19], v[170:173], v[202:205], v[16:19]
	v_mfma_f32_16x16x32_bf16 v[4:7], v[158:161], v[210:213], v[4:7]
	v_mfma_f32_16x16x32_bf16 v[0:3], v[170:173], v[210:213], v[0:3]
	v_mfma_f32_16x16x32_bf16 v[48:51], v[158:161], v[186:189], v[48:51]
	v_mfma_f32_16x16x32_bf16 v[52:55], v[170:173], v[186:189], v[52:55]
	s_barrier
	s_add_i32 s59, 0, 0x18000
	s_add_i32 s60, 0, 0x1c000
	v_add_u32_e32 v68, s59, v167
	v_add_u32_e32 v170, s60, v167
	ds_read_b128 v[56:59], v68
	ds_read_b128 v[60:63], v68 offset:1024
	ds_read_b128 v[64:67], v68 offset:2048
	ds_read_b128 v[68:71], v68 offset:3072
	ds_read_b128 v[154:157], v170
	ds_read_b128 v[158:161], v170 offset:1024
	ds_read_b128 v[162:165], v170 offset:2048
	ds_read_b128 v[170:173], v170 offset:3072
	s_add_u32 s8, s30, 0xb0000
	s_addc_u32 s9, s31, 0
	s_mov_b32 m0, s45
	v_lshl_add_u64 v[216:217], s[8:9], 0, v[144:145]
	ds_read_b128 v[178:181], v169 offset:32768
	ds_read_b128 v[186:189], v169 offset:33792
	ds_read_b128 v[190:193], v169 offset:34816
	ds_read_b128 v[194:197], v169 offset:35840
	ds_read_b128 v[198:201], v169 offset:36864
	ds_read_b128 v[202:205], v169 offset:37888
	ds_read_b128 v[206:209], v169 offset:38912
	ds_read_b128 v[210:213], v169 offset:39936
	global_load_lds_dwordx4 v[216:217], off
	v_lshl_add_u64 v[216:217], s[8:9], 0, v[146:147]
	s_mov_b32 m0, s46
	s_nop 0
	global_load_lds_dwordx4 v[216:217], off
	s_waitcnt vmcnt(8)
	s_waitcnt lgkmcnt(0)
	s_barrier
	s_waitcnt lgkmcnt(0)
	v_mfma_f32_16x16x32_bf16 v[140:143], v[56:59], v[178:181], v[140:143]
	v_mfma_f32_16x16x32_bf16 v[136:139], v[64:67], v[178:181], v[136:139]
	v_mfma_f32_16x16x32_bf16 v[124:127], v[56:59], v[190:193], v[124:127]
	v_mfma_f32_16x16x32_bf16 v[120:123], v[64:67], v[190:193], v[120:123]
	v_mfma_f32_16x16x32_bf16 v[108:111], v[56:59], v[198:201], v[108:111]
	v_mfma_f32_16x16x32_bf16 v[104:107], v[64:67], v[198:201], v[104:107]
	v_mfma_f32_16x16x32_bf16 v[92:95], v[56:59], v[206:209], v[92:95]
	v_mfma_f32_16x16x32_bf16 v[88:91], v[64:67], v[206:209], v[88:91]
	v_mfma_f32_16x16x32_bf16 v[140:143], v[60:63], v[186:189], v[140:143]
	v_mfma_f32_16x16x32_bf16 v[136:139], v[68:71], v[186:189], v[136:139]
	v_mfma_f32_16x16x32_bf16 v[124:127], v[60:63], v[194:197], v[124:127]
	v_mfma_f32_16x16x32_bf16 v[120:123], v[68:71], v[194:197], v[120:123]
	v_mfma_f32_16x16x32_bf16 v[108:111], v[60:63], v[202:205], v[108:111]
	v_mfma_f32_16x16x32_bf16 v[104:107], v[68:71], v[202:205], v[104:107]
	v_mfma_f32_16x16x32_bf16 v[92:95], v[60:63], v[210:213], v[92:95]
	v_mfma_f32_16x16x32_bf16 v[88:91], v[68:71], v[210:213], v[88:91]
	v_mfma_f32_16x16x32_bf16 v[132:135], v[154:157], v[178:181], v[132:135]
	v_mfma_f32_16x16x32_bf16 v[128:131], v[162:165], v[178:181], v[128:131]
	v_mfma_f32_16x16x32_bf16 v[116:119], v[154:157], v[190:193], v[116:119]
	v_mfma_f32_16x16x32_bf16 v[112:115], v[162:165], v[190:193], v[112:115]
	v_mfma_f32_16x16x32_bf16 v[100:103], v[154:157], v[198:201], v[100:103]
	v_mfma_f32_16x16x32_bf16 v[96:99], v[162:165], v[198:201], v[96:99]
	v_mfma_f32_16x16x32_bf16 v[84:87], v[154:157], v[206:209], v[84:87]
	v_mfma_f32_16x16x32_bf16 v[80:83], v[162:165], v[206:209], v[80:83]
	v_mfma_f32_16x16x32_bf16 v[132:135], v[158:161], v[186:189], v[132:135]
	v_mfma_f32_16x16x32_bf16 v[128:131], v[170:173], v[186:189], v[128:131]
	v_mfma_f32_16x16x32_bf16 v[116:119], v[158:161], v[194:197], v[116:119]
	v_mfma_f32_16x16x32_bf16 v[112:115], v[170:173], v[194:197], v[112:115]
	v_mfma_f32_16x16x32_bf16 v[100:103], v[158:161], v[202:205], v[100:103]
	v_mfma_f32_16x16x32_bf16 v[96:99], v[170:173], v[202:205], v[96:99]
	v_mfma_f32_16x16x32_bf16 v[84:87], v[158:161], v[210:213], v[84:87]
	v_mfma_f32_16x16x32_bf16 v[80:83], v[170:173], v[210:213], v[80:83]
	s_barrier
	s_add_i32 s8, s59, s40
	v_lshl_add_u64 v[174:175], v[174:175], 0, s[72:73]
	s_mov_b32 m0, s8
	ds_read_b128 v[178:181], v169 offset:49152
	ds_read_b128 v[186:189], v169 offset:50176
	ds_read_b128 v[190:193], v169 offset:51200
	ds_read_b128 v[194:197], v169 offset:52224
	ds_read_b128 v[198:201], v169 offset:53248
	ds_read_b128 v[202:205], v169 offset:54272
	ds_read_b128 v[206:209], v169 offset:55296
	ds_read_b128 v[210:213], v169 offset:56320
	global_load_lds_dwordx4 v[174:175], off
	s_add_i32 m0, s8, 0x2000
	s_add_u32 s8, s28, 0xb0080
	v_lshl_add_u64 v[174:175], v[182:183], 0, s[72:73]
	s_addc_u32 s9, s29, 0
	s_add_i32 s28, s60, s40
	global_load_lds_dwordx4 v[174:175], off
	v_lshl_add_u64 v[174:175], s[8:9], 0, v[176:177]
	s_mov_b32 m0, s28
	s_nop 0
	global_load_lds_dwordx4 v[174:175], off
	v_lshl_add_u64 v[174:175], s[8:9], 0, v[148:149]
	s_add_i32 m0, s28, 0x2000
	s_nop 0
	global_load_lds_dwordx4 v[174:175], off
	v_lshl_add_u64 v[174:175], v[184:185], 0, s[72:73]
	s_mov_b32 m0, s48
	s_nop 0
	global_load_lds_dwordx4 v[174:175], off
	v_lshl_add_u64 v[174:175], v[214:215], 0, s[72:73]
	s_mov_b32 m0, s49
	s_nop 0
	global_load_lds_dwordx4 v[174:175], off
	s_waitcnt vmcnt(8)
	s_waitcnt lgkmcnt(0)
	s_barrier
	s_waitcnt lgkmcnt(0)
	v_mfma_f32_16x16x32_bf16 v[76:79], v[56:59], v[178:181], v[76:79]
	v_mfma_f32_16x16x32_bf16 v[72:75], v[64:67], v[178:181], v[72:75]
	v_mfma_f32_16x16x32_bf16 v[44:47], v[56:59], v[190:193], v[44:47]
	v_mfma_f32_16x16x32_bf16 v[40:43], v[64:67], v[190:193], v[40:43]
	v_mfma_f32_16x16x32_bf16 v[28:31], v[56:59], v[198:201], v[28:31]
	v_mfma_f32_16x16x32_bf16 v[24:27], v[64:67], v[198:201], v[24:27]
	v_mfma_f32_16x16x32_bf16 v[12:15], v[56:59], v[206:209], v[12:15]
	v_mfma_f32_16x16x32_bf16 v[8:11], v[64:67], v[206:209], v[8:11]
	v_mfma_f32_16x16x32_bf16 v[76:79], v[60:63], v[186:189], v[76:79]
	v_mfma_f32_16x16x32_bf16 v[72:75], v[68:71], v[186:189], v[72:75]
	v_mfma_f32_16x16x32_bf16 v[44:47], v[60:63], v[194:197], v[44:47]
	v_mfma_f32_16x16x32_bf16 v[40:43], v[68:71], v[194:197], v[40:43]
	v_mfma_f32_16x16x32_bf16 v[28:31], v[60:63], v[202:205], v[28:31]
	v_mfma_f32_16x16x32_bf16 v[24:27], v[68:71], v[202:205], v[24:27]
	v_mfma_f32_16x16x32_bf16 v[12:15], v[60:63], v[210:213], v[12:15]
	v_mfma_f32_16x16x32_bf16 v[8:11], v[68:71], v[210:213], v[8:11]
	v_mfma_f32_16x16x32_bf16 v[48:51], v[154:157], v[178:181], v[48:51]
	v_mfma_f32_16x16x32_bf16 v[60:63], v[158:161], v[186:189], v[48:51]
	v_mfma_f32_16x16x32_bf16 v[48:51], v[162:165], v[178:181], v[52:55]
	v_mfma_f32_16x16x32_bf16 v[36:39], v[154:157], v[190:193], v[36:39]
	v_mfma_f32_16x16x32_bf16 v[32:35], v[162:165], v[190:193], v[32:35]
	v_mfma_f32_16x16x32_bf16 v[20:23], v[154:157], v[198:201], v[20:23]
	v_mfma_f32_16x16x32_bf16 v[16:19], v[162:165], v[198:201], v[16:19]
	v_mfma_f32_16x16x32_bf16 v[4:7], v[154:157], v[206:209], v[4:7]
	v_mfma_f32_16x16x32_bf16 v[0:3], v[162:165], v[206:209], v[0:3]
	v_mfma_f32_16x16x32_bf16 v[56:59], v[170:173], v[186:189], v[48:51]
	v_mfma_f32_16x16x32_bf16 v[36:39], v[158:161], v[194:197], v[36:39]
	v_mfma_f32_16x16x32_bf16 v[32:35], v[170:173], v[194:197], v[32:35]
	v_mfma_f32_16x16x32_bf16 v[20:23], v[158:161], v[202:205], v[20:23]
	v_mfma_f32_16x16x32_bf16 v[16:19], v[170:173], v[202:205], v[16:19]
	v_mfma_f32_16x16x32_bf16 v[4:7], v[158:161], v[210:213], v[4:7]
	v_mfma_f32_16x16x32_bf16 v[0:3], v[170:173], v[210:213], v[0:3]
	s_barrier
	s_add_i32 s58, s58, 2
	s_add_u32 s50, s50, 0x100
	s_addc_u32 s57, s57, 0
	s_cmp_gt_u32 s58, 41
	s_mov_b64 s[8:9], s[6:7]
	s_cbranch_scc0 .LBB0_1901
	s_and_b64 vcc, exec, s[22:23]
	s_cbranch_vccz .LBB0_1904
	s_barrier
